# v18: v17 + P6b lane-bit-2 Hadamard stage without the sign-flip xors: add_dpp on banks 0,2 / sub_dpp on banks 1,3 (172 VALU ops per row fewer, same IEEE results)
# speedup vs baseline: 1.0006x; 1.0006x over previous
.LBB0_909:
	s_waitcnt lgkmcnt(0)
	v_lshl_add_u64 v[4:5], s[8:9], 0, v[2:3]
	v_add_co_u32_e32 v24, vcc, 0x23000000, v4
	s_nop 1
	v_addc_co_u32_e32 v25, vcc, 0, v5, vcc
	global_load_dwordx2 v[86:87], v[24:25], off nt
	v_add_co_u32_e32 v54, vcc, s24, v4
	s_nop 1
	v_addc_co_u32_e32 v55, vcc, 0, v5, vcc
	v_add_co_u32_e32 v88, vcc, s25, v4
	s_nop 1
	v_addc_co_u32_e32 v89, vcc, 0, v5, vcc
	v_add_co_u32_e32 v90, vcc, s26, v4
	s_nop 1
	v_addc_co_u32_e32 v91, vcc, 0, v5, vcc
	global_load_dwordx2 v[36:37], v[54:55], off offset:1024 nt
	global_load_dwordx2 v[34:35], v[54:55], off offset:1536 nt
	global_load_dwordx2 v[32:33], v[54:55], off offset:2048 nt
	global_load_dwordx2 v[30:31], v[54:55], off offset:2560 nt
	global_load_dwordx2 v[22:23], v[88:89], off offset:512 nt
	global_load_dwordx2 v[20:21], v[88:89], off offset:1024 nt
	global_load_dwordx2 v[18:19], v[88:89], off offset:1536 nt
	global_load_dwordx2 v[16:17], v[88:89], off offset:2048 nt
	global_load_dwordx2 v[14:15], v[88:89], off offset:2560 nt
	global_load_dwordx2 v[12:13], v[88:89], off offset:3072 nt
	global_load_dwordx2 v[10:11], v[88:89], off offset:3584 nt
	global_load_dwordx2 v[28:29], v[54:55], off offset:3072 nt
	global_load_dwordx2 v[26:27], v[54:55], off offset:3584 nt
	global_load_dwordx2 v[8:9], v[90:91], off nt
	global_load_dwordx2 v[6:7], v[90:91], off offset:512 nt
	global_load_dwordx2 v[92:93], v[24:25], off offset:512 nt
	global_load_dwordx2 v[94:95], v[24:25], off offset:1024 nt
	global_load_dwordx2 v[96:97], v[24:25], off offset:1536 nt
	global_load_dwordx2 v[80:81], v[24:25], off offset:2048 nt
	global_load_dwordx2 v[78:79], v[24:25], off offset:2560 nt
	global_load_dwordx2 v[76:77], v[24:25], off offset:3072 nt
	global_load_dwordx2 v[74:75], v[24:25], off offset:3584 nt
	v_add_co_u32_e32 v56, vcc, s22, v4
	s_nop 1
	v_addc_co_u32_e32 v57, vcc, 0, v5, vcc
	v_add_co_u32_e32 v98, vcc, s23, v4
	s_nop 1
	v_addc_co_u32_e32 v99, vcc, 0, v5, vcc
	global_load_dwordx2 v[70:71], v[56:57], off offset:512 nt
	global_load_dwordx2 v[68:69], v[56:57], off offset:1024 nt
	global_load_dwordx2 v[66:67], v[56:57], off offset:1536 nt
	global_load_dwordx2 v[64:65], v[56:57], off offset:2048 nt
	global_load_dwordx2 v[62:63], v[56:57], off offset:2560 nt
	global_load_dwordx2 v[60:61], v[56:57], off offset:3072 nt
	global_load_dwordx2 v[58:59], v[56:57], off offset:3584 nt
	global_load_dwordx2 v[38:39], v[54:55], off offset:512 nt
	global_load_dwordx2 v[52:53], v[98:99], off offset:1024 nt
	global_load_dwordx2 v[50:51], v[98:99], off offset:1536 nt
	global_load_dwordx2 v[48:49], v[98:99], off offset:2048 nt
	global_load_dwordx2 v[46:47], v[98:99], off offset:2560 nt
	global_load_dwordx2 v[44:45], v[98:99], off offset:3072 nt
	global_load_dwordx2 v[42:43], v[98:99], off offset:3584 nt
	global_load_dwordx2 v[40:41], v[88:89], off offset:-4096 nt
	global_load_dwordx2 v[24:25], v[88:89], off nt
	global_load_dwordx2 v[72:73], v[98:99], off offset:-4096 nt
	global_load_dwordx2 v[56:57], v[98:99], off nt
	global_load_dwordx2 v[54:55], v[98:99], off offset:512 nt
	global_load_dwordx2 v[4:5], v[90:91], off offset:1024 nt
	s_waitcnt vmcnt(42)
	v_lshlrev_b32_e32 v88, 16, v86
	v_and_b32_e32 v86, 0xffff0000, v86
	v_lshlrev_b32_e32 v89, 16, v87
	v_and_b32_e32 v87, 0xffff0000, v87
	v_add_f32_e32 v90, v88, v86
	v_sub_f32_e32 v86, v88, v86
	v_add_f32_e32 v88, v89, v87
	v_sub_f32_e32 v87, v89, v87
	v_add_f32_e32 v89, v90, v88
	v_add_f32_e32 v91, v86, v87
	v_sub_f32_e32 v88, v90, v88
	v_sub_f32_e32 v86, v86, v87
	v_xor_b32_e32 v204, v82, v89
	v_xor_b32_e32 v205, v82, v91
	v_xor_b32_e32 v206, v82, v88
	v_xor_b32_e32 v207, v82, v86
	v_add_f32_dpp v87, v89, v204 quad_perm:[1,0,3,2] row_mask:0xf bank_mask:0xf bound_ctrl:1
	v_add_f32_dpp v89, v91, v205 quad_perm:[1,0,3,2] row_mask:0xf bank_mask:0xf bound_ctrl:1
	v_add_f32_dpp v88, v88, v206 quad_perm:[1,0,3,2] row_mask:0xf bank_mask:0xf bound_ctrl:1
	v_add_f32_dpp v86, v86, v207 quad_perm:[1,0,3,2] row_mask:0xf bank_mask:0xf bound_ctrl:1
	v_xor_b32_e32 v200, v83, v87
	v_xor_b32_e32 v201, v83, v89
	v_xor_b32_e32 v202, v83, v88
	v_xor_b32_e32 v203, v83, v86
	v_add_f32_dpp v204, v87, v200 quad_perm:[2,3,0,1] row_mask:0xf bank_mask:0xf bound_ctrl:1
	v_add_f32_dpp v205, v89, v201 quad_perm:[2,3,0,1] row_mask:0xf bank_mask:0xf bound_ctrl:1
	v_add_f32_dpp v206, v88, v202 quad_perm:[2,3,0,1] row_mask:0xf bank_mask:0xf bound_ctrl:1
	v_add_f32_dpp v207, v86, v203 quad_perm:[2,3,0,1] row_mask:0xf bank_mask:0xf bound_ctrl:1
	v_add_f32_dpp v87, v204, v204 row_shl:4 row_mask:0xf bank_mask:0x5
	v_add_f32_dpp v89, v205, v205 row_shl:4 row_mask:0xf bank_mask:0x5
	v_add_f32_dpp v88, v206, v206 row_shl:4 row_mask:0xf bank_mask:0x5
	v_add_f32_dpp v90, v207, v207 row_shl:4 row_mask:0xf bank_mask:0x5
	v_sub_f32_dpp v87, v204, v204 row_shr:4 row_mask:0xf bank_mask:0xa
	v_sub_f32_dpp v89, v205, v205 row_shr:4 row_mask:0xf bank_mask:0xa
	v_sub_f32_dpp v88, v206, v206 row_shr:4 row_mask:0xf bank_mask:0xa
	v_sub_f32_dpp v90, v207, v207 row_shr:4 row_mask:0xf bank_mask:0xa
	v_max_f32_e64 v86, |v87|, |v89|
	v_max_f32_e64 v91, |v88|, |v90|
	v_max3_f32 v91, v86, 0, v91
	v_cvt_pk_bf16_f32 v86, v87, v89
	v_cvt_pk_bf16_f32 v87, v88, v90
	s_waitcnt vmcnt(26)
	v_lshlrev_b32_e32 v88, 16, v92
	v_and_b32_e32 v89, 0xffff0000, v92
	v_lshlrev_b32_e32 v90, 16, v93
	v_and_b32_e32 v92, 0xffff0000, v93
	v_add_f32_e32 v93, v88, v89
	v_sub_f32_e32 v88, v88, v89
	v_add_f32_e32 v89, v90, v92
	v_sub_f32_e32 v90, v90, v92
	v_add_f32_e32 v92, v93, v89
	v_sub_f32_e32 v89, v93, v89
	v_add_f32_e32 v98, v88, v90
	v_sub_f32_e32 v88, v88, v90
	v_xor_b32_e32 v204, v82, v92
	v_xor_b32_e32 v205, v82, v89
	v_xor_b32_e32 v206, v82, v98
	v_xor_b32_e32 v207, v82, v88
	v_add_f32_dpp v90, v92, v204 quad_perm:[1,0,3,2] row_mask:0xf bank_mask:0xf bound_ctrl:1
	v_add_f32_dpp v89, v89, v205 quad_perm:[1,0,3,2] row_mask:0xf bank_mask:0xf bound_ctrl:1
	v_add_f32_dpp v92, v98, v206 quad_perm:[1,0,3,2] row_mask:0xf bank_mask:0xf bound_ctrl:1
	v_add_f32_dpp v88, v88, v207 quad_perm:[1,0,3,2] row_mask:0xf bank_mask:0xf bound_ctrl:1
	v_xor_b32_e32 v200, v83, v90
	v_xor_b32_e32 v201, v83, v92
	v_xor_b32_e32 v202, v83, v89
	v_xor_b32_e32 v203, v83, v88
	v_add_f32_dpp v204, v90, v200 quad_perm:[2,3,0,1] row_mask:0xf bank_mask:0xf bound_ctrl:1
	v_add_f32_dpp v205, v92, v201 quad_perm:[2,3,0,1] row_mask:0xf bank_mask:0xf bound_ctrl:1
	v_add_f32_dpp v206, v89, v202 quad_perm:[2,3,0,1] row_mask:0xf bank_mask:0xf bound_ctrl:1
	v_add_f32_dpp v207, v88, v203 quad_perm:[2,3,0,1] row_mask:0xf bank_mask:0xf bound_ctrl:1
	v_add_f32_dpp v90, v204, v204 row_shl:4 row_mask:0xf bank_mask:0x5
	v_add_f32_dpp v92, v205, v205 row_shl:4 row_mask:0xf bank_mask:0x5
	v_add_f32_dpp v89, v206, v206 row_shl:4 row_mask:0xf bank_mask:0x5
	v_add_f32_dpp v93, v207, v207 row_shl:4 row_mask:0xf bank_mask:0x5
	v_sub_f32_dpp v90, v204, v204 row_shr:4 row_mask:0xf bank_mask:0xa
	v_sub_f32_dpp v92, v205, v205 row_shr:4 row_mask:0xf bank_mask:0xa
	v_sub_f32_dpp v89, v206, v206 row_shr:4 row_mask:0xf bank_mask:0xa
	v_sub_f32_dpp v93, v207, v207 row_shr:4 row_mask:0xf bank_mask:0xa
	v_max_f32_e64 v88, |v90|, |v92|
	v_max_f32_e64 v98, |v89|, |v93|
	v_max3_f32 v91, v91, v88, v98
	v_cvt_pk_bf16_f32 v88, v90, v92
	v_cvt_pk_bf16_f32 v89, v89, v93
	s_waitcnt vmcnt(25)
	v_lshlrev_b32_e32 v90, 16, v94
	v_and_b32_e32 v92, 0xffff0000, v94
	v_lshlrev_b32_e32 v93, 16, v95
	v_and_b32_e32 v94, 0xffff0000, v95
	v_add_f32_e32 v95, v90, v92
	v_sub_f32_e32 v90, v90, v92
	v_add_f32_e32 v92, v93, v94
	v_sub_f32_e32 v93, v93, v94
	v_add_f32_e32 v94, v95, v92
	v_sub_f32_e32 v92, v95, v92
	v_add_f32_e32 v98, v90, v93
	v_sub_f32_e32 v90, v90, v93
	v_xor_b32_e32 v204, v82, v94
	v_xor_b32_e32 v205, v82, v92
	v_xor_b32_e32 v206, v82, v98
	v_xor_b32_e32 v207, v82, v90
	v_add_f32_dpp v93, v94, v204 quad_perm:[1,0,3,2] row_mask:0xf bank_mask:0xf bound_ctrl:1
	v_add_f32_dpp v92, v92, v205 quad_perm:[1,0,3,2] row_mask:0xf bank_mask:0xf bound_ctrl:1
	v_add_f32_dpp v94, v98, v206 quad_perm:[1,0,3,2] row_mask:0xf bank_mask:0xf bound_ctrl:1
	v_add_f32_dpp v90, v90, v207 quad_perm:[1,0,3,2] row_mask:0xf bank_mask:0xf bound_ctrl:1
	v_xor_b32_e32 v200, v83, v93
	v_xor_b32_e32 v201, v83, v94
	v_xor_b32_e32 v202, v83, v92
	v_xor_b32_e32 v203, v83, v90
	v_add_f32_dpp v204, v93, v200 quad_perm:[2,3,0,1] row_mask:0xf bank_mask:0xf bound_ctrl:1
	v_add_f32_dpp v205, v94, v201 quad_perm:[2,3,0,1] row_mask:0xf bank_mask:0xf bound_ctrl:1
	v_add_f32_dpp v206, v92, v202 quad_perm:[2,3,0,1] row_mask:0xf bank_mask:0xf bound_ctrl:1
	v_add_f32_dpp v207, v90, v203 quad_perm:[2,3,0,1] row_mask:0xf bank_mask:0xf bound_ctrl:1
	v_add_f32_dpp v93, v204, v204 row_shl:4 row_mask:0xf bank_mask:0x5
	v_add_f32_dpp v94, v205, v205 row_shl:4 row_mask:0xf bank_mask:0x5
	v_add_f32_dpp v92, v206, v206 row_shl:4 row_mask:0xf bank_mask:0x5
	v_add_f32_dpp v95, v207, v207 row_shl:4 row_mask:0xf bank_mask:0x5
	v_sub_f32_dpp v93, v204, v204 row_shr:4 row_mask:0xf bank_mask:0xa
	v_sub_f32_dpp v94, v205, v205 row_shr:4 row_mask:0xf bank_mask:0xa
	v_sub_f32_dpp v92, v206, v206 row_shr:4 row_mask:0xf bank_mask:0xa
	v_sub_f32_dpp v95, v207, v207 row_shr:4 row_mask:0xf bank_mask:0xa
	v_max_f32_e64 v90, |v93|, |v94|
	v_max_f32_e64 v98, |v92|, |v95|
	v_max3_f32 v98, v91, v90, v98
	v_cvt_pk_bf16_f32 v90, v93, v94
	v_cvt_pk_bf16_f32 v91, v92, v95
	s_waitcnt vmcnt(24)
	v_lshlrev_b32_e32 v92, 16, v96
	v_and_b32_e32 v93, 0xffff0000, v96
	v_lshlrev_b32_e32 v94, 16, v97
	v_and_b32_e32 v95, 0xffff0000, v97
	v_add_f32_e32 v96, v92, v93
	v_sub_f32_e32 v92, v92, v93
	v_add_f32_e32 v93, v94, v95
	v_sub_f32_e32 v94, v94, v95
	v_add_f32_e32 v95, v96, v93
	v_sub_f32_e32 v93, v96, v93
	v_add_f32_e32 v97, v92, v94
	v_sub_f32_e32 v92, v92, v94
	v_xor_b32_e32 v204, v82, v95
	v_xor_b32_e32 v205, v82, v93
	v_xor_b32_e32 v206, v82, v97
	v_xor_b32_e32 v207, v82, v92
	v_add_f32_dpp v94, v95, v204 quad_perm:[1,0,3,2] row_mask:0xf bank_mask:0xf bound_ctrl:1
	v_add_f32_dpp v93, v93, v205 quad_perm:[1,0,3,2] row_mask:0xf bank_mask:0xf bound_ctrl:1
	v_add_f32_dpp v95, v97, v206 quad_perm:[1,0,3,2] row_mask:0xf bank_mask:0xf bound_ctrl:1
	v_add_f32_dpp v92, v92, v207 quad_perm:[1,0,3,2] row_mask:0xf bank_mask:0xf bound_ctrl:1
	v_xor_b32_e32 v200, v83, v94
	v_xor_b32_e32 v201, v83, v95
	v_xor_b32_e32 v202, v83, v93
	v_xor_b32_e32 v203, v83, v92
	v_add_f32_dpp v204, v94, v200 quad_perm:[2,3,0,1] row_mask:0xf bank_mask:0xf bound_ctrl:1
	v_add_f32_dpp v205, v95, v201 quad_perm:[2,3,0,1] row_mask:0xf bank_mask:0xf bound_ctrl:1
	v_add_f32_dpp v206, v93, v202 quad_perm:[2,3,0,1] row_mask:0xf bank_mask:0xf bound_ctrl:1
	v_add_f32_dpp v207, v92, v203 quad_perm:[2,3,0,1] row_mask:0xf bank_mask:0xf bound_ctrl:1
	v_add_f32_dpp v94, v204, v204 row_shl:4 row_mask:0xf bank_mask:0x5
	v_add_f32_dpp v95, v205, v205 row_shl:4 row_mask:0xf bank_mask:0x5
	v_add_f32_dpp v93, v206, v206 row_shl:4 row_mask:0xf bank_mask:0x5
	v_add_f32_dpp v96, v207, v207 row_shl:4 row_mask:0xf bank_mask:0x5
	v_sub_f32_dpp v94, v204, v204 row_shr:4 row_mask:0xf bank_mask:0xa
	v_sub_f32_dpp v95, v205, v205 row_shr:4 row_mask:0xf bank_mask:0xa
	v_sub_f32_dpp v93, v206, v206 row_shr:4 row_mask:0xf bank_mask:0xa
	v_sub_f32_dpp v96, v207, v207 row_shr:4 row_mask:0xf bank_mask:0xa
	v_max_f32_e64 v92, |v94|, |v95|
	v_max_f32_e64 v97, |v93|, |v96|
	v_max3_f32 v97, v98, v92, v97
	v_cvt_pk_bf16_f32 v92, v94, v95
	s_waitcnt vmcnt(23)
	v_lshlrev_b32_e32 v94, 16, v80
	v_and_b32_e32 v80, 0xffff0000, v80
	v_lshlrev_b32_e32 v95, 16, v81
	v_and_b32_e32 v81, 0xffff0000, v81
	v_cvt_pk_bf16_f32 v93, v93, v96
	v_add_f32_e32 v96, v94, v80
	v_sub_f32_e32 v80, v94, v80
	v_add_f32_e32 v94, v95, v81
	v_sub_f32_e32 v81, v95, v81
	v_add_f32_e32 v95, v96, v94
	v_sub_f32_e32 v94, v96, v94
	v_add_f32_e32 v98, v80, v81
	v_sub_f32_e32 v80, v80, v81
	v_xor_b32_e32 v204, v82, v95
	v_xor_b32_e32 v205, v82, v94
	v_xor_b32_e32 v206, v82, v98
	v_xor_b32_e32 v207, v82, v80
	v_add_f32_dpp v81, v95, v204 quad_perm:[1,0,3,2] row_mask:0xf bank_mask:0xf bound_ctrl:1
	v_add_f32_dpp v94, v94, v205 quad_perm:[1,0,3,2] row_mask:0xf bank_mask:0xf bound_ctrl:1
	v_add_f32_dpp v95, v98, v206 quad_perm:[1,0,3,2] row_mask:0xf bank_mask:0xf bound_ctrl:1
	v_add_f32_dpp v80, v80, v207 quad_perm:[1,0,3,2] row_mask:0xf bank_mask:0xf bound_ctrl:1
	v_xor_b32_e32 v200, v83, v81
	v_xor_b32_e32 v201, v83, v95
	v_xor_b32_e32 v202, v83, v94
	v_xor_b32_e32 v203, v83, v80
	v_add_f32_dpp v204, v81, v200 quad_perm:[2,3,0,1] row_mask:0xf bank_mask:0xf bound_ctrl:1
	v_add_f32_dpp v205, v95, v201 quad_perm:[2,3,0,1] row_mask:0xf bank_mask:0xf bound_ctrl:1
	v_add_f32_dpp v206, v94, v202 quad_perm:[2,3,0,1] row_mask:0xf bank_mask:0xf bound_ctrl:1
	v_add_f32_dpp v207, v80, v203 quad_perm:[2,3,0,1] row_mask:0xf bank_mask:0xf bound_ctrl:1
	v_add_f32_dpp v81, v204, v204 row_shl:4 row_mask:0xf bank_mask:0x5
	v_add_f32_dpp v95, v205, v205 row_shl:4 row_mask:0xf bank_mask:0x5
	v_add_f32_dpp v94, v206, v206 row_shl:4 row_mask:0xf bank_mask:0x5
	v_add_f32_dpp v96, v207, v207 row_shl:4 row_mask:0xf bank_mask:0x5
	v_sub_f32_dpp v81, v204, v204 row_shr:4 row_mask:0xf bank_mask:0xa
	v_sub_f32_dpp v95, v205, v205 row_shr:4 row_mask:0xf bank_mask:0xa
	v_sub_f32_dpp v94, v206, v206 row_shr:4 row_mask:0xf bank_mask:0xa
	v_sub_f32_dpp v96, v207, v207 row_shr:4 row_mask:0xf bank_mask:0xa
	v_max_f32_e64 v80, |v81|, |v95|
	v_max_f32_e64 v98, |v94|, |v96|
	v_max3_f32 v97, v97, v80, v98
	v_cvt_pk_bf16_f32 v80, v81, v95
	v_cvt_pk_bf16_f32 v81, v94, v96
	s_waitcnt vmcnt(22)
	v_lshlrev_b32_e32 v94, 16, v78
	v_and_b32_e32 v78, 0xffff0000, v78
	v_lshlrev_b32_e32 v95, 16, v79
	v_and_b32_e32 v79, 0xffff0000, v79
	v_add_f32_e32 v96, v94, v78
	v_sub_f32_e32 v78, v94, v78
	v_add_f32_e32 v94, v95, v79
	v_sub_f32_e32 v79, v95, v79
	v_add_f32_e32 v95, v96, v94
	v_sub_f32_e32 v94, v96, v94
	v_add_f32_e32 v98, v78, v79
	v_sub_f32_e32 v78, v78, v79
	v_xor_b32_e32 v204, v82, v95
	v_xor_b32_e32 v205, v82, v94
	v_xor_b32_e32 v206, v82, v98
	v_xor_b32_e32 v207, v82, v78
	v_add_f32_dpp v79, v95, v204 quad_perm:[1,0,3,2] row_mask:0xf bank_mask:0xf bound_ctrl:1
	v_add_f32_dpp v94, v94, v205 quad_perm:[1,0,3,2] row_mask:0xf bank_mask:0xf bound_ctrl:1
	v_add_f32_dpp v95, v98, v206 quad_perm:[1,0,3,2] row_mask:0xf bank_mask:0xf bound_ctrl:1
	v_add_f32_dpp v78, v78, v207 quad_perm:[1,0,3,2] row_mask:0xf bank_mask:0xf bound_ctrl:1
	v_xor_b32_e32 v200, v83, v79
	v_xor_b32_e32 v201, v83, v95
	v_xor_b32_e32 v202, v83, v94
	v_xor_b32_e32 v203, v83, v78
	v_add_f32_dpp v204, v79, v200 quad_perm:[2,3,0,1] row_mask:0xf bank_mask:0xf bound_ctrl:1
	v_add_f32_dpp v205, v95, v201 quad_perm:[2,3,0,1] row_mask:0xf bank_mask:0xf bound_ctrl:1
	v_add_f32_dpp v206, v94, v202 quad_perm:[2,3,0,1] row_mask:0xf bank_mask:0xf bound_ctrl:1
	v_add_f32_dpp v207, v78, v203 quad_perm:[2,3,0,1] row_mask:0xf bank_mask:0xf bound_ctrl:1
	v_add_f32_dpp v79, v204, v204 row_shl:4 row_mask:0xf bank_mask:0x5
	v_add_f32_dpp v95, v205, v205 row_shl:4 row_mask:0xf bank_mask:0x5
	v_add_f32_dpp v94, v206, v206 row_shl:4 row_mask:0xf bank_mask:0x5
	v_add_f32_dpp v96, v207, v207 row_shl:4 row_mask:0xf bank_mask:0x5
	v_sub_f32_dpp v79, v204, v204 row_shr:4 row_mask:0xf bank_mask:0xa
	v_sub_f32_dpp v95, v205, v205 row_shr:4 row_mask:0xf bank_mask:0xa
	v_sub_f32_dpp v94, v206, v206 row_shr:4 row_mask:0xf bank_mask:0xa
	v_sub_f32_dpp v96, v207, v207 row_shr:4 row_mask:0xf bank_mask:0xa
	v_max_f32_e64 v78, |v79|, |v95|
	v_max_f32_e64 v98, |v94|, |v96|
	v_max3_f32 v97, v97, v78, v98
	v_cvt_pk_bf16_f32 v78, v79, v95
	v_cvt_pk_bf16_f32 v79, v94, v96
	s_waitcnt vmcnt(21)
	v_lshlrev_b32_e32 v94, 16, v76
	v_and_b32_e32 v76, 0xffff0000, v76
	v_lshlrev_b32_e32 v95, 16, v77
	v_and_b32_e32 v77, 0xffff0000, v77
	v_add_f32_e32 v96, v94, v76
	v_sub_f32_e32 v76, v94, v76
	v_add_f32_e32 v94, v95, v77
	v_sub_f32_e32 v77, v95, v77
	v_add_f32_e32 v95, v96, v94
	v_sub_f32_e32 v94, v96, v94
	v_add_f32_e32 v98, v76, v77
	v_sub_f32_e32 v76, v76, v77
	v_xor_b32_e32 v204, v82, v95
	v_xor_b32_e32 v205, v82, v94
	v_xor_b32_e32 v206, v82, v98
	v_xor_b32_e32 v207, v82, v76
	v_add_f32_dpp v77, v95, v204 quad_perm:[1,0,3,2] row_mask:0xf bank_mask:0xf bound_ctrl:1
	v_add_f32_dpp v94, v94, v205 quad_perm:[1,0,3,2] row_mask:0xf bank_mask:0xf bound_ctrl:1
	v_add_f32_dpp v95, v98, v206 quad_perm:[1,0,3,2] row_mask:0xf bank_mask:0xf bound_ctrl:1
	v_add_f32_dpp v76, v76, v207 quad_perm:[1,0,3,2] row_mask:0xf bank_mask:0xf bound_ctrl:1
	v_xor_b32_e32 v200, v83, v77
	v_xor_b32_e32 v201, v83, v95
	v_xor_b32_e32 v202, v83, v94
	v_xor_b32_e32 v203, v83, v76
	v_add_f32_dpp v204, v77, v200 quad_perm:[2,3,0,1] row_mask:0xf bank_mask:0xf bound_ctrl:1
	v_add_f32_dpp v205, v95, v201 quad_perm:[2,3,0,1] row_mask:0xf bank_mask:0xf bound_ctrl:1
	v_add_f32_dpp v206, v94, v202 quad_perm:[2,3,0,1] row_mask:0xf bank_mask:0xf bound_ctrl:1
	v_add_f32_dpp v207, v76, v203 quad_perm:[2,3,0,1] row_mask:0xf bank_mask:0xf bound_ctrl:1
	v_add_f32_dpp v77, v204, v204 row_shl:4 row_mask:0xf bank_mask:0x5
	v_add_f32_dpp v95, v205, v205 row_shl:4 row_mask:0xf bank_mask:0x5
	v_add_f32_dpp v94, v206, v206 row_shl:4 row_mask:0xf bank_mask:0x5
	v_add_f32_dpp v96, v207, v207 row_shl:4 row_mask:0xf bank_mask:0x5
	v_sub_f32_dpp v77, v204, v204 row_shr:4 row_mask:0xf bank_mask:0xa
	v_sub_f32_dpp v95, v205, v205 row_shr:4 row_mask:0xf bank_mask:0xa
	v_sub_f32_dpp v94, v206, v206 row_shr:4 row_mask:0xf bank_mask:0xa
	v_sub_f32_dpp v96, v207, v207 row_shr:4 row_mask:0xf bank_mask:0xa
	v_max_f32_e64 v76, |v77|, |v95|
	v_max_f32_e64 v98, |v94|, |v96|
	v_max3_f32 v97, v97, v76, v98
	v_cvt_pk_bf16_f32 v76, v77, v95
	v_cvt_pk_bf16_f32 v77, v94, v96
	s_waitcnt vmcnt(20)
	v_lshlrev_b32_e32 v94, 16, v74
	v_and_b32_e32 v74, 0xffff0000, v74
	v_lshlrev_b32_e32 v95, 16, v75
	v_and_b32_e32 v75, 0xffff0000, v75
	v_add_f32_e32 v96, v94, v74
	v_sub_f32_e32 v74, v94, v74
	v_add_f32_e32 v94, v95, v75
	v_sub_f32_e32 v75, v95, v75
	v_add_f32_e32 v95, v96, v94
	v_sub_f32_e32 v94, v96, v94
	v_add_f32_e32 v98, v74, v75
	v_sub_f32_e32 v74, v74, v75
	v_xor_b32_e32 v204, v82, v95
	v_xor_b32_e32 v205, v82, v94
	v_xor_b32_e32 v206, v82, v98
	v_xor_b32_e32 v207, v82, v74
	v_add_f32_dpp v75, v95, v204 quad_perm:[1,0,3,2] row_mask:0xf bank_mask:0xf bound_ctrl:1
	v_add_f32_dpp v94, v94, v205 quad_perm:[1,0,3,2] row_mask:0xf bank_mask:0xf bound_ctrl:1
	v_add_f32_dpp v95, v98, v206 quad_perm:[1,0,3,2] row_mask:0xf bank_mask:0xf bound_ctrl:1
	v_add_f32_dpp v74, v74, v207 quad_perm:[1,0,3,2] row_mask:0xf bank_mask:0xf bound_ctrl:1
	v_xor_b32_e32 v200, v83, v75
	v_xor_b32_e32 v201, v83, v95
	v_xor_b32_e32 v202, v83, v94
	v_xor_b32_e32 v203, v83, v74
	v_add_f32_dpp v204, v75, v200 quad_perm:[2,3,0,1] row_mask:0xf bank_mask:0xf bound_ctrl:1
	v_add_f32_dpp v205, v95, v201 quad_perm:[2,3,0,1] row_mask:0xf bank_mask:0xf bound_ctrl:1
	v_add_f32_dpp v206, v94, v202 quad_perm:[2,3,0,1] row_mask:0xf bank_mask:0xf bound_ctrl:1
	v_add_f32_dpp v207, v74, v203 quad_perm:[2,3,0,1] row_mask:0xf bank_mask:0xf bound_ctrl:1
	v_add_f32_dpp v75, v204, v204 row_shl:4 row_mask:0xf bank_mask:0x5
	v_add_f32_dpp v95, v205, v205 row_shl:4 row_mask:0xf bank_mask:0x5
	v_add_f32_dpp v94, v206, v206 row_shl:4 row_mask:0xf bank_mask:0x5
	v_add_f32_dpp v96, v207, v207 row_shl:4 row_mask:0xf bank_mask:0x5
	v_sub_f32_dpp v75, v204, v204 row_shr:4 row_mask:0xf bank_mask:0xa
	v_sub_f32_dpp v95, v205, v205 row_shr:4 row_mask:0xf bank_mask:0xa
	v_sub_f32_dpp v94, v206, v206 row_shr:4 row_mask:0xf bank_mask:0xa
	v_sub_f32_dpp v96, v207, v207 row_shr:4 row_mask:0xf bank_mask:0xa
	v_max_f32_e64 v74, |v75|, |v95|
	v_max_f32_e64 v98, |v94|, |v96|
	v_max3_f32 v97, v97, v74, v98
	v_cvt_pk_bf16_f32 v74, v75, v95
	v_cvt_pk_bf16_f32 v75, v94, v96
	s_waitcnt vmcnt(3)
	v_lshlrev_b32_e32 v94, 16, v72
	v_and_b32_e32 v72, 0xffff0000, v72
	v_lshlrev_b32_e32 v95, 16, v73
	v_and_b32_e32 v73, 0xffff0000, v73
	v_add_f32_e32 v96, v94, v72
	v_sub_f32_e32 v72, v94, v72
	v_add_f32_e32 v94, v95, v73
	v_sub_f32_e32 v73, v95, v73
	v_add_f32_e32 v95, v96, v94
	v_sub_f32_e32 v94, v96, v94
	v_add_f32_e32 v98, v72, v73
	v_sub_f32_e32 v72, v72, v73
	v_xor_b32_e32 v204, v82, v95
	v_xor_b32_e32 v205, v82, v94
	v_xor_b32_e32 v206, v82, v98
	v_xor_b32_e32 v207, v82, v72
	v_add_f32_dpp v73, v95, v204 quad_perm:[1,0,3,2] row_mask:0xf bank_mask:0xf bound_ctrl:1
	v_add_f32_dpp v94, v94, v205 quad_perm:[1,0,3,2] row_mask:0xf bank_mask:0xf bound_ctrl:1
	v_add_f32_dpp v95, v98, v206 quad_perm:[1,0,3,2] row_mask:0xf bank_mask:0xf bound_ctrl:1
	v_add_f32_dpp v72, v72, v207 quad_perm:[1,0,3,2] row_mask:0xf bank_mask:0xf bound_ctrl:1
	v_xor_b32_e32 v200, v83, v73
	v_xor_b32_e32 v201, v83, v95
	v_xor_b32_e32 v202, v83, v94
	v_xor_b32_e32 v203, v83, v72
	v_add_f32_dpp v204, v73, v200 quad_perm:[2,3,0,1] row_mask:0xf bank_mask:0xf bound_ctrl:1
	v_add_f32_dpp v205, v95, v201 quad_perm:[2,3,0,1] row_mask:0xf bank_mask:0xf bound_ctrl:1
	v_add_f32_dpp v206, v94, v202 quad_perm:[2,3,0,1] row_mask:0xf bank_mask:0xf bound_ctrl:1
	v_add_f32_dpp v207, v72, v203 quad_perm:[2,3,0,1] row_mask:0xf bank_mask:0xf bound_ctrl:1
	v_add_f32_dpp v73, v204, v204 row_shl:4 row_mask:0xf bank_mask:0x5
	v_add_f32_dpp v95, v205, v205 row_shl:4 row_mask:0xf bank_mask:0x5
	v_add_f32_dpp v94, v206, v206 row_shl:4 row_mask:0xf bank_mask:0x5
	v_add_f32_dpp v96, v207, v207 row_shl:4 row_mask:0xf bank_mask:0x5
	v_sub_f32_dpp v73, v204, v204 row_shr:4 row_mask:0xf bank_mask:0xa
	v_sub_f32_dpp v95, v205, v205 row_shr:4 row_mask:0xf bank_mask:0xa
	v_sub_f32_dpp v94, v206, v206 row_shr:4 row_mask:0xf bank_mask:0xa
	v_sub_f32_dpp v96, v207, v207 row_shr:4 row_mask:0xf bank_mask:0xa
	v_max_f32_e64 v72, |v73|, |v95|
	v_max_f32_e64 v98, |v94|, |v96|
	v_max3_f32 v97, v97, v72, v98
	v_cvt_pk_bf16_f32 v72, v73, v95
	v_cvt_pk_bf16_f32 v73, v94, v96
	v_lshlrev_b32_e32 v94, 16, v70
	v_and_b32_e32 v70, 0xffff0000, v70
	v_lshlrev_b32_e32 v95, 16, v71
	v_and_b32_e32 v71, 0xffff0000, v71
	v_add_f32_e32 v96, v94, v70
	v_sub_f32_e32 v70, v94, v70
	v_add_f32_e32 v94, v95, v71
	v_sub_f32_e32 v71, v95, v71
	v_add_f32_e32 v95, v96, v94
	v_sub_f32_e32 v94, v96, v94
	v_add_f32_e32 v98, v70, v71
	v_sub_f32_e32 v70, v70, v71
	v_xor_b32_e32 v204, v82, v95
	v_xor_b32_e32 v205, v82, v94
	v_xor_b32_e32 v206, v82, v98
	v_xor_b32_e32 v207, v82, v70
	v_add_f32_dpp v71, v95, v204 quad_perm:[1,0,3,2] row_mask:0xf bank_mask:0xf bound_ctrl:1
	v_add_f32_dpp v94, v94, v205 quad_perm:[1,0,3,2] row_mask:0xf bank_mask:0xf bound_ctrl:1
	v_add_f32_dpp v95, v98, v206 quad_perm:[1,0,3,2] row_mask:0xf bank_mask:0xf bound_ctrl:1
	v_add_f32_dpp v70, v70, v207 quad_perm:[1,0,3,2] row_mask:0xf bank_mask:0xf bound_ctrl:1
	v_xor_b32_e32 v200, v83, v71
	v_xor_b32_e32 v201, v83, v95
	v_xor_b32_e32 v202, v83, v94
	v_xor_b32_e32 v203, v83, v70
	v_add_f32_dpp v204, v71, v200 quad_perm:[2,3,0,1] row_mask:0xf bank_mask:0xf bound_ctrl:1
	v_add_f32_dpp v205, v95, v201 quad_perm:[2,3,0,1] row_mask:0xf bank_mask:0xf bound_ctrl:1
	v_add_f32_dpp v206, v94, v202 quad_perm:[2,3,0,1] row_mask:0xf bank_mask:0xf bound_ctrl:1
	v_add_f32_dpp v207, v70, v203 quad_perm:[2,3,0,1] row_mask:0xf bank_mask:0xf bound_ctrl:1
	v_add_f32_dpp v71, v204, v204 row_shl:4 row_mask:0xf bank_mask:0x5
	v_add_f32_dpp v95, v205, v205 row_shl:4 row_mask:0xf bank_mask:0x5
	v_add_f32_dpp v94, v206, v206 row_shl:4 row_mask:0xf bank_mask:0x5
	v_add_f32_dpp v96, v207, v207 row_shl:4 row_mask:0xf bank_mask:0x5
	v_sub_f32_dpp v71, v204, v204 row_shr:4 row_mask:0xf bank_mask:0xa
	v_sub_f32_dpp v95, v205, v205 row_shr:4 row_mask:0xf bank_mask:0xa
	v_sub_f32_dpp v94, v206, v206 row_shr:4 row_mask:0xf bank_mask:0xa
	v_sub_f32_dpp v96, v207, v207 row_shr:4 row_mask:0xf bank_mask:0xa
	v_max_f32_e64 v70, |v71|, |v95|
	v_max_f32_e64 v98, |v94|, |v96|
	v_max3_f32 v97, v97, v70, v98
	v_cvt_pk_bf16_f32 v70, v71, v95
	v_cvt_pk_bf16_f32 v71, v94, v96
	v_lshlrev_b32_e32 v94, 16, v68
	v_and_b32_e32 v68, 0xffff0000, v68
	v_lshlrev_b32_e32 v95, 16, v69
	v_and_b32_e32 v69, 0xffff0000, v69
	v_add_f32_e32 v96, v94, v68
	v_sub_f32_e32 v68, v94, v68
	v_add_f32_e32 v94, v95, v69
	v_sub_f32_e32 v69, v95, v69
	v_add_f32_e32 v95, v96, v94
	v_sub_f32_e32 v94, v96, v94
	v_add_f32_e32 v98, v68, v69
	v_sub_f32_e32 v68, v68, v69
	v_xor_b32_e32 v204, v82, v95
	v_xor_b32_e32 v205, v82, v94
	v_xor_b32_e32 v206, v82, v98
	v_xor_b32_e32 v207, v82, v68
	v_add_f32_dpp v69, v95, v204 quad_perm:[1,0,3,2] row_mask:0xf bank_mask:0xf bound_ctrl:1
	v_add_f32_dpp v94, v94, v205 quad_perm:[1,0,3,2] row_mask:0xf bank_mask:0xf bound_ctrl:1
	v_add_f32_dpp v95, v98, v206 quad_perm:[1,0,3,2] row_mask:0xf bank_mask:0xf bound_ctrl:1
	v_add_f32_dpp v68, v68, v207 quad_perm:[1,0,3,2] row_mask:0xf bank_mask:0xf bound_ctrl:1
	v_xor_b32_e32 v200, v83, v69
	v_xor_b32_e32 v201, v83, v95
	v_xor_b32_e32 v202, v83, v94
	v_xor_b32_e32 v203, v83, v68
	v_add_f32_dpp v204, v69, v200 quad_perm:[2,3,0,1] row_mask:0xf bank_mask:0xf bound_ctrl:1
	v_add_f32_dpp v205, v95, v201 quad_perm:[2,3,0,1] row_mask:0xf bank_mask:0xf bound_ctrl:1
	v_add_f32_dpp v206, v94, v202 quad_perm:[2,3,0,1] row_mask:0xf bank_mask:0xf bound_ctrl:1
	v_add_f32_dpp v207, v68, v203 quad_perm:[2,3,0,1] row_mask:0xf bank_mask:0xf bound_ctrl:1
	v_add_f32_dpp v69, v204, v204 row_shl:4 row_mask:0xf bank_mask:0x5
	v_add_f32_dpp v95, v205, v205 row_shl:4 row_mask:0xf bank_mask:0x5
	v_add_f32_dpp v94, v206, v206 row_shl:4 row_mask:0xf bank_mask:0x5
	v_add_f32_dpp v96, v207, v207 row_shl:4 row_mask:0xf bank_mask:0x5
	v_sub_f32_dpp v69, v204, v204 row_shr:4 row_mask:0xf bank_mask:0xa
	v_sub_f32_dpp v95, v205, v205 row_shr:4 row_mask:0xf bank_mask:0xa
	v_sub_f32_dpp v94, v206, v206 row_shr:4 row_mask:0xf bank_mask:0xa
	v_sub_f32_dpp v96, v207, v207 row_shr:4 row_mask:0xf bank_mask:0xa
	v_max_f32_e64 v68, |v69|, |v95|
	v_max_f32_e64 v98, |v94|, |v96|
	v_max3_f32 v97, v97, v68, v98
	v_cvt_pk_bf16_f32 v68, v69, v95
	v_cvt_pk_bf16_f32 v69, v94, v96
	v_lshlrev_b32_e32 v94, 16, v66
	v_and_b32_e32 v66, 0xffff0000, v66
	v_lshlrev_b32_e32 v95, 16, v67
	v_and_b32_e32 v67, 0xffff0000, v67
	v_add_f32_e32 v96, v94, v66
	v_sub_f32_e32 v66, v94, v66
	v_add_f32_e32 v94, v95, v67
	v_sub_f32_e32 v67, v95, v67
	v_add_f32_e32 v95, v96, v94
	v_sub_f32_e32 v94, v96, v94
	v_add_f32_e32 v98, v66, v67
	v_sub_f32_e32 v66, v66, v67
	v_xor_b32_e32 v204, v82, v95
	v_xor_b32_e32 v205, v82, v94
	v_xor_b32_e32 v206, v82, v98
	v_xor_b32_e32 v207, v82, v66
	v_add_f32_dpp v67, v95, v204 quad_perm:[1,0,3,2] row_mask:0xf bank_mask:0xf bound_ctrl:1
	v_add_f32_dpp v94, v94, v205 quad_perm:[1,0,3,2] row_mask:0xf bank_mask:0xf bound_ctrl:1
	v_add_f32_dpp v95, v98, v206 quad_perm:[1,0,3,2] row_mask:0xf bank_mask:0xf bound_ctrl:1
	v_add_f32_dpp v66, v66, v207 quad_perm:[1,0,3,2] row_mask:0xf bank_mask:0xf bound_ctrl:1
	v_xor_b32_e32 v200, v83, v67
	v_xor_b32_e32 v201, v83, v95
	v_xor_b32_e32 v202, v83, v94
	v_xor_b32_e32 v203, v83, v66
	v_add_f32_dpp v204, v67, v200 quad_perm:[2,3,0,1] row_mask:0xf bank_mask:0xf bound_ctrl:1
	v_add_f32_dpp v205, v95, v201 quad_perm:[2,3,0,1] row_mask:0xf bank_mask:0xf bound_ctrl:1
	v_add_f32_dpp v206, v94, v202 quad_perm:[2,3,0,1] row_mask:0xf bank_mask:0xf bound_ctrl:1
	v_add_f32_dpp v207, v66, v203 quad_perm:[2,3,0,1] row_mask:0xf bank_mask:0xf bound_ctrl:1
	v_add_f32_dpp v67, v204, v204 row_shl:4 row_mask:0xf bank_mask:0x5
	v_add_f32_dpp v95, v205, v205 row_shl:4 row_mask:0xf bank_mask:0x5
	v_add_f32_dpp v94, v206, v206 row_shl:4 row_mask:0xf bank_mask:0x5
	v_add_f32_dpp v96, v207, v207 row_shl:4 row_mask:0xf bank_mask:0x5
	v_sub_f32_dpp v67, v204, v204 row_shr:4 row_mask:0xf bank_mask:0xa
	v_sub_f32_dpp v95, v205, v205 row_shr:4 row_mask:0xf bank_mask:0xa
	v_sub_f32_dpp v94, v206, v206 row_shr:4 row_mask:0xf bank_mask:0xa
	v_sub_f32_dpp v96, v207, v207 row_shr:4 row_mask:0xf bank_mask:0xa
	v_max_f32_e64 v66, |v67|, |v95|
	v_max_f32_e64 v98, |v94|, |v96|
	v_max3_f32 v97, v97, v66, v98
	v_cvt_pk_bf16_f32 v66, v67, v95
	v_cvt_pk_bf16_f32 v67, v94, v96
	v_lshlrev_b32_e32 v94, 16, v64
	v_and_b32_e32 v64, 0xffff0000, v64
	v_lshlrev_b32_e32 v95, 16, v65
	v_and_b32_e32 v65, 0xffff0000, v65
	v_add_f32_e32 v96, v94, v64
	v_sub_f32_e32 v64, v94, v64
	v_add_f32_e32 v94, v95, v65
	v_sub_f32_e32 v65, v95, v65
	v_add_f32_e32 v95, v96, v94
	v_sub_f32_e32 v94, v96, v94
	v_add_f32_e32 v98, v64, v65
	v_sub_f32_e32 v64, v64, v65
	v_xor_b32_e32 v204, v82, v95
	v_xor_b32_e32 v205, v82, v94
	v_xor_b32_e32 v206, v82, v98
	v_xor_b32_e32 v207, v82, v64
	v_add_f32_dpp v65, v95, v204 quad_perm:[1,0,3,2] row_mask:0xf bank_mask:0xf bound_ctrl:1
	v_add_f32_dpp v94, v94, v205 quad_perm:[1,0,3,2] row_mask:0xf bank_mask:0xf bound_ctrl:1
	v_add_f32_dpp v95, v98, v206 quad_perm:[1,0,3,2] row_mask:0xf bank_mask:0xf bound_ctrl:1
	v_add_f32_dpp v64, v64, v207 quad_perm:[1,0,3,2] row_mask:0xf bank_mask:0xf bound_ctrl:1
	v_xor_b32_e32 v200, v83, v65
	v_xor_b32_e32 v201, v83, v95
	v_xor_b32_e32 v202, v83, v94
	v_xor_b32_e32 v203, v83, v64
	v_add_f32_dpp v204, v65, v200 quad_perm:[2,3,0,1] row_mask:0xf bank_mask:0xf bound_ctrl:1
	v_add_f32_dpp v205, v95, v201 quad_perm:[2,3,0,1] row_mask:0xf bank_mask:0xf bound_ctrl:1
	v_add_f32_dpp v206, v94, v202 quad_perm:[2,3,0,1] row_mask:0xf bank_mask:0xf bound_ctrl:1
	v_add_f32_dpp v207, v64, v203 quad_perm:[2,3,0,1] row_mask:0xf bank_mask:0xf bound_ctrl:1
	v_add_f32_dpp v65, v204, v204 row_shl:4 row_mask:0xf bank_mask:0x5
	v_add_f32_dpp v95, v205, v205 row_shl:4 row_mask:0xf bank_mask:0x5
	v_add_f32_dpp v94, v206, v206 row_shl:4 row_mask:0xf bank_mask:0x5
	v_add_f32_dpp v96, v207, v207 row_shl:4 row_mask:0xf bank_mask:0x5
	v_sub_f32_dpp v65, v204, v204 row_shr:4 row_mask:0xf bank_mask:0xa
	v_sub_f32_dpp v95, v205, v205 row_shr:4 row_mask:0xf bank_mask:0xa
	v_sub_f32_dpp v94, v206, v206 row_shr:4 row_mask:0xf bank_mask:0xa
	v_sub_f32_dpp v96, v207, v207 row_shr:4 row_mask:0xf bank_mask:0xa
	v_max_f32_e64 v64, |v65|, |v95|
	v_max_f32_e64 v98, |v94|, |v96|
	v_max3_f32 v97, v97, v64, v98
	v_cvt_pk_bf16_f32 v64, v65, v95
	v_cvt_pk_bf16_f32 v65, v94, v96
	v_lshlrev_b32_e32 v94, 16, v62
	v_and_b32_e32 v62, 0xffff0000, v62
	v_lshlrev_b32_e32 v95, 16, v63
	v_and_b32_e32 v63, 0xffff0000, v63
	v_add_f32_e32 v96, v94, v62
	v_sub_f32_e32 v62, v94, v62
	v_add_f32_e32 v94, v95, v63
	v_sub_f32_e32 v63, v95, v63
	v_add_f32_e32 v95, v96, v94
	v_sub_f32_e32 v94, v96, v94
	v_add_f32_e32 v98, v62, v63
	v_sub_f32_e32 v62, v62, v63
	v_xor_b32_e32 v204, v82, v95
	v_xor_b32_e32 v205, v82, v94
	v_xor_b32_e32 v206, v82, v98
	v_xor_b32_e32 v207, v82, v62
	v_add_f32_dpp v63, v95, v204 quad_perm:[1,0,3,2] row_mask:0xf bank_mask:0xf bound_ctrl:1
	v_add_f32_dpp v94, v94, v205 quad_perm:[1,0,3,2] row_mask:0xf bank_mask:0xf bound_ctrl:1
	v_add_f32_dpp v95, v98, v206 quad_perm:[1,0,3,2] row_mask:0xf bank_mask:0xf bound_ctrl:1
	v_add_f32_dpp v62, v62, v207 quad_perm:[1,0,3,2] row_mask:0xf bank_mask:0xf bound_ctrl:1
	v_xor_b32_e32 v200, v83, v63
	v_xor_b32_e32 v201, v83, v95
	v_xor_b32_e32 v202, v83, v94
	v_xor_b32_e32 v203, v83, v62
	v_add_f32_dpp v204, v63, v200 quad_perm:[2,3,0,1] row_mask:0xf bank_mask:0xf bound_ctrl:1
	v_add_f32_dpp v205, v95, v201 quad_perm:[2,3,0,1] row_mask:0xf bank_mask:0xf bound_ctrl:1
	v_add_f32_dpp v206, v94, v202 quad_perm:[2,3,0,1] row_mask:0xf bank_mask:0xf bound_ctrl:1
	v_add_f32_dpp v207, v62, v203 quad_perm:[2,3,0,1] row_mask:0xf bank_mask:0xf bound_ctrl:1
	v_add_f32_dpp v63, v204, v204 row_shl:4 row_mask:0xf bank_mask:0x5
	v_add_f32_dpp v95, v205, v205 row_shl:4 row_mask:0xf bank_mask:0x5
	v_add_f32_dpp v94, v206, v206 row_shl:4 row_mask:0xf bank_mask:0x5
	v_add_f32_dpp v96, v207, v207 row_shl:4 row_mask:0xf bank_mask:0x5
	v_sub_f32_dpp v63, v204, v204 row_shr:4 row_mask:0xf bank_mask:0xa
	v_sub_f32_dpp v95, v205, v205 row_shr:4 row_mask:0xf bank_mask:0xa
	v_sub_f32_dpp v94, v206, v206 row_shr:4 row_mask:0xf bank_mask:0xa
	v_sub_f32_dpp v96, v207, v207 row_shr:4 row_mask:0xf bank_mask:0xa
	v_max_f32_e64 v62, |v63|, |v95|
	v_max_f32_e64 v98, |v94|, |v96|
	v_max3_f32 v97, v97, v62, v98
	v_cvt_pk_bf16_f32 v62, v63, v95
	v_cvt_pk_bf16_f32 v63, v94, v96
	v_lshlrev_b32_e32 v94, 16, v60
	v_and_b32_e32 v60, 0xffff0000, v60
	v_lshlrev_b32_e32 v95, 16, v61
	v_and_b32_e32 v61, 0xffff0000, v61
	v_add_f32_e32 v96, v94, v60
	v_sub_f32_e32 v60, v94, v60
	v_add_f32_e32 v94, v95, v61
	v_sub_f32_e32 v61, v95, v61
	v_add_f32_e32 v95, v96, v94
	v_sub_f32_e32 v94, v96, v94
	v_add_f32_e32 v98, v60, v61
	v_sub_f32_e32 v60, v60, v61
	v_xor_b32_e32 v204, v82, v95
	v_xor_b32_e32 v205, v82, v94
	v_xor_b32_e32 v206, v82, v98
	v_xor_b32_e32 v207, v82, v60
	v_add_f32_dpp v61, v95, v204 quad_perm:[1,0,3,2] row_mask:0xf bank_mask:0xf bound_ctrl:1
	v_add_f32_dpp v94, v94, v205 quad_perm:[1,0,3,2] row_mask:0xf bank_mask:0xf bound_ctrl:1
	v_add_f32_dpp v95, v98, v206 quad_perm:[1,0,3,2] row_mask:0xf bank_mask:0xf bound_ctrl:1
	v_add_f32_dpp v60, v60, v207 quad_perm:[1,0,3,2] row_mask:0xf bank_mask:0xf bound_ctrl:1
	v_xor_b32_e32 v200, v83, v61
	v_xor_b32_e32 v201, v83, v95
	v_xor_b32_e32 v202, v83, v94
	v_xor_b32_e32 v203, v83, v60
	v_add_f32_dpp v204, v61, v200 quad_perm:[2,3,0,1] row_mask:0xf bank_mask:0xf bound_ctrl:1
	v_add_f32_dpp v205, v95, v201 quad_perm:[2,3,0,1] row_mask:0xf bank_mask:0xf bound_ctrl:1
	v_add_f32_dpp v206, v94, v202 quad_perm:[2,3,0,1] row_mask:0xf bank_mask:0xf bound_ctrl:1
	v_add_f32_dpp v207, v60, v203 quad_perm:[2,3,0,1] row_mask:0xf bank_mask:0xf bound_ctrl:1
	v_add_f32_dpp v61, v204, v204 row_shl:4 row_mask:0xf bank_mask:0x5
	v_add_f32_dpp v95, v205, v205 row_shl:4 row_mask:0xf bank_mask:0x5
	v_add_f32_dpp v94, v206, v206 row_shl:4 row_mask:0xf bank_mask:0x5
	v_add_f32_dpp v96, v207, v207 row_shl:4 row_mask:0xf bank_mask:0x5
	v_sub_f32_dpp v61, v204, v204 row_shr:4 row_mask:0xf bank_mask:0xa
	v_sub_f32_dpp v95, v205, v205 row_shr:4 row_mask:0xf bank_mask:0xa
	v_sub_f32_dpp v94, v206, v206 row_shr:4 row_mask:0xf bank_mask:0xa
	v_sub_f32_dpp v96, v207, v207 row_shr:4 row_mask:0xf bank_mask:0xa
	v_max_f32_e64 v60, |v61|, |v95|
	v_max_f32_e64 v98, |v94|, |v96|
	v_max3_f32 v97, v97, v60, v98
	v_cvt_pk_bf16_f32 v60, v61, v95
	v_cvt_pk_bf16_f32 v61, v94, v96
	v_lshlrev_b32_e32 v94, 16, v58
	v_and_b32_e32 v58, 0xffff0000, v58
	v_lshlrev_b32_e32 v95, 16, v59
	v_and_b32_e32 v59, 0xffff0000, v59
	v_add_f32_e32 v96, v94, v58
	v_sub_f32_e32 v58, v94, v58
	v_add_f32_e32 v94, v95, v59
	v_sub_f32_e32 v59, v95, v59
	v_add_f32_e32 v95, v96, v94
	v_sub_f32_e32 v94, v96, v94
	v_add_f32_e32 v98, v58, v59
	v_sub_f32_e32 v58, v58, v59
	v_xor_b32_e32 v204, v82, v95
	v_xor_b32_e32 v205, v82, v94
	v_xor_b32_e32 v206, v82, v98
	v_xor_b32_e32 v207, v82, v58
	v_add_f32_dpp v59, v95, v204 quad_perm:[1,0,3,2] row_mask:0xf bank_mask:0xf bound_ctrl:1
	v_add_f32_dpp v94, v94, v205 quad_perm:[1,0,3,2] row_mask:0xf bank_mask:0xf bound_ctrl:1
	v_add_f32_dpp v95, v98, v206 quad_perm:[1,0,3,2] row_mask:0xf bank_mask:0xf bound_ctrl:1
	v_add_f32_dpp v58, v58, v207 quad_perm:[1,0,3,2] row_mask:0xf bank_mask:0xf bound_ctrl:1
	v_xor_b32_e32 v200, v83, v59
	v_xor_b32_e32 v201, v83, v95
	v_xor_b32_e32 v202, v83, v94
	v_xor_b32_e32 v203, v83, v58
	v_add_f32_dpp v204, v59, v200 quad_perm:[2,3,0,1] row_mask:0xf bank_mask:0xf bound_ctrl:1
	v_add_f32_dpp v205, v95, v201 quad_perm:[2,3,0,1] row_mask:0xf bank_mask:0xf bound_ctrl:1
	v_add_f32_dpp v206, v94, v202 quad_perm:[2,3,0,1] row_mask:0xf bank_mask:0xf bound_ctrl:1
	v_add_f32_dpp v207, v58, v203 quad_perm:[2,3,0,1] row_mask:0xf bank_mask:0xf bound_ctrl:1
	v_add_f32_dpp v59, v204, v204 row_shl:4 row_mask:0xf bank_mask:0x5
	v_add_f32_dpp v95, v205, v205 row_shl:4 row_mask:0xf bank_mask:0x5
	v_add_f32_dpp v94, v206, v206 row_shl:4 row_mask:0xf bank_mask:0x5
	v_add_f32_dpp v96, v207, v207 row_shl:4 row_mask:0xf bank_mask:0x5
	v_sub_f32_dpp v59, v204, v204 row_shr:4 row_mask:0xf bank_mask:0xa
	v_sub_f32_dpp v95, v205, v205 row_shr:4 row_mask:0xf bank_mask:0xa
	v_sub_f32_dpp v94, v206, v206 row_shr:4 row_mask:0xf bank_mask:0xa
	v_sub_f32_dpp v96, v207, v207 row_shr:4 row_mask:0xf bank_mask:0xa
	v_max_f32_e64 v58, |v59|, |v95|
	v_max_f32_e64 v98, |v94|, |v96|
	v_max3_f32 v97, v97, v58, v98
	v_cvt_pk_bf16_f32 v58, v59, v95
	v_cvt_pk_bf16_f32 v59, v94, v96
	s_waitcnt vmcnt(2)
	v_lshlrev_b32_e32 v94, 16, v56
	v_and_b32_e32 v56, 0xffff0000, v56
	v_lshlrev_b32_e32 v95, 16, v57
	v_and_b32_e32 v57, 0xffff0000, v57
	v_add_f32_e32 v96, v94, v56
	v_sub_f32_e32 v56, v94, v56
	v_add_f32_e32 v94, v95, v57
	v_sub_f32_e32 v57, v95, v57
	v_add_f32_e32 v95, v96, v94
	v_sub_f32_e32 v94, v96, v94
	v_add_f32_e32 v98, v56, v57
	v_sub_f32_e32 v56, v56, v57
	v_xor_b32_e32 v204, v82, v95
	v_xor_b32_e32 v205, v82, v94
	v_xor_b32_e32 v206, v82, v98
	v_xor_b32_e32 v207, v82, v56
	v_add_f32_dpp v57, v95, v204 quad_perm:[1,0,3,2] row_mask:0xf bank_mask:0xf bound_ctrl:1
	v_add_f32_dpp v94, v94, v205 quad_perm:[1,0,3,2] row_mask:0xf bank_mask:0xf bound_ctrl:1
	v_add_f32_dpp v95, v98, v206 quad_perm:[1,0,3,2] row_mask:0xf bank_mask:0xf bound_ctrl:1
	v_add_f32_dpp v56, v56, v207 quad_perm:[1,0,3,2] row_mask:0xf bank_mask:0xf bound_ctrl:1
	v_xor_b32_e32 v200, v83, v57
	v_xor_b32_e32 v201, v83, v95
	v_xor_b32_e32 v202, v83, v94
	v_xor_b32_e32 v203, v83, v56
	v_add_f32_dpp v204, v57, v200 quad_perm:[2,3,0,1] row_mask:0xf bank_mask:0xf bound_ctrl:1
	v_add_f32_dpp v205, v95, v201 quad_perm:[2,3,0,1] row_mask:0xf bank_mask:0xf bound_ctrl:1
	v_add_f32_dpp v206, v94, v202 quad_perm:[2,3,0,1] row_mask:0xf bank_mask:0xf bound_ctrl:1
	v_add_f32_dpp v207, v56, v203 quad_perm:[2,3,0,1] row_mask:0xf bank_mask:0xf bound_ctrl:1
	v_add_f32_dpp v57, v204, v204 row_shl:4 row_mask:0xf bank_mask:0x5
	v_add_f32_dpp v95, v205, v205 row_shl:4 row_mask:0xf bank_mask:0x5
	v_add_f32_dpp v94, v206, v206 row_shl:4 row_mask:0xf bank_mask:0x5
	v_add_f32_dpp v96, v207, v207 row_shl:4 row_mask:0xf bank_mask:0x5
	v_sub_f32_dpp v57, v204, v204 row_shr:4 row_mask:0xf bank_mask:0xa
	v_sub_f32_dpp v95, v205, v205 row_shr:4 row_mask:0xf bank_mask:0xa
	v_sub_f32_dpp v94, v206, v206 row_shr:4 row_mask:0xf bank_mask:0xa
	v_sub_f32_dpp v96, v207, v207 row_shr:4 row_mask:0xf bank_mask:0xa
	v_max_f32_e64 v56, |v57|, |v95|
	v_max_f32_e64 v98, |v94|, |v96|
	v_max3_f32 v97, v97, v56, v98
	v_cvt_pk_bf16_f32 v56, v57, v95
	v_cvt_pk_bf16_f32 v57, v94, v96
	s_waitcnt vmcnt(1)
	v_lshlrev_b32_e32 v94, 16, v54
	v_and_b32_e32 v54, 0xffff0000, v54
	v_lshlrev_b32_e32 v95, 16, v55
	v_and_b32_e32 v55, 0xffff0000, v55
	v_add_f32_e32 v96, v94, v54
	v_sub_f32_e32 v54, v94, v54
	v_add_f32_e32 v94, v95, v55
	v_sub_f32_e32 v55, v95, v55
	v_add_f32_e32 v95, v96, v94
	v_sub_f32_e32 v94, v96, v94
	v_add_f32_e32 v98, v54, v55
	v_sub_f32_e32 v54, v54, v55
	v_xor_b32_e32 v204, v82, v95
	v_xor_b32_e32 v205, v82, v94
	v_xor_b32_e32 v206, v82, v98
	v_xor_b32_e32 v207, v82, v54
	v_add_f32_dpp v55, v95, v204 quad_perm:[1,0,3,2] row_mask:0xf bank_mask:0xf bound_ctrl:1
	v_add_f32_dpp v94, v94, v205 quad_perm:[1,0,3,2] row_mask:0xf bank_mask:0xf bound_ctrl:1
	v_add_f32_dpp v95, v98, v206 quad_perm:[1,0,3,2] row_mask:0xf bank_mask:0xf bound_ctrl:1
	v_add_f32_dpp v54, v54, v207 quad_perm:[1,0,3,2] row_mask:0xf bank_mask:0xf bound_ctrl:1
	v_xor_b32_e32 v200, v83, v55
	v_xor_b32_e32 v201, v83, v95
	v_xor_b32_e32 v202, v83, v94
	v_xor_b32_e32 v203, v83, v54
	v_add_f32_dpp v204, v55, v200 quad_perm:[2,3,0,1] row_mask:0xf bank_mask:0xf bound_ctrl:1
	v_add_f32_dpp v205, v95, v201 quad_perm:[2,3,0,1] row_mask:0xf bank_mask:0xf bound_ctrl:1
	v_add_f32_dpp v206, v94, v202 quad_perm:[2,3,0,1] row_mask:0xf bank_mask:0xf bound_ctrl:1
	v_add_f32_dpp v207, v54, v203 quad_perm:[2,3,0,1] row_mask:0xf bank_mask:0xf bound_ctrl:1
	v_add_f32_dpp v55, v204, v204 row_shl:4 row_mask:0xf bank_mask:0x5
	v_add_f32_dpp v95, v205, v205 row_shl:4 row_mask:0xf bank_mask:0x5
	v_add_f32_dpp v94, v206, v206 row_shl:4 row_mask:0xf bank_mask:0x5
	v_add_f32_dpp v96, v207, v207 row_shl:4 row_mask:0xf bank_mask:0x5
	v_sub_f32_dpp v55, v204, v204 row_shr:4 row_mask:0xf bank_mask:0xa
	v_sub_f32_dpp v95, v205, v205 row_shr:4 row_mask:0xf bank_mask:0xa
	v_sub_f32_dpp v94, v206, v206 row_shr:4 row_mask:0xf bank_mask:0xa
	v_sub_f32_dpp v96, v207, v207 row_shr:4 row_mask:0xf bank_mask:0xa
	v_max_f32_e64 v54, |v55|, |v95|
	v_max_f32_e64 v98, |v94|, |v96|
	v_max3_f32 v97, v97, v54, v98
	v_cvt_pk_bf16_f32 v54, v55, v95
	v_cvt_pk_bf16_f32 v55, v94, v96
	v_lshlrev_b32_e32 v94, 16, v52
	v_and_b32_e32 v52, 0xffff0000, v52
	v_lshlrev_b32_e32 v95, 16, v53
	v_and_b32_e32 v53, 0xffff0000, v53
	v_add_f32_e32 v96, v94, v52
	v_sub_f32_e32 v52, v94, v52
	v_add_f32_e32 v94, v95, v53
	v_sub_f32_e32 v53, v95, v53
	v_add_f32_e32 v95, v96, v94
	v_sub_f32_e32 v94, v96, v94
	v_add_f32_e32 v98, v52, v53
	v_sub_f32_e32 v52, v52, v53
	v_xor_b32_e32 v204, v82, v95
	v_xor_b32_e32 v205, v82, v94
	v_xor_b32_e32 v206, v82, v98
	v_xor_b32_e32 v207, v82, v52
	v_add_f32_dpp v53, v95, v204 quad_perm:[1,0,3,2] row_mask:0xf bank_mask:0xf bound_ctrl:1
	v_add_f32_dpp v94, v94, v205 quad_perm:[1,0,3,2] row_mask:0xf bank_mask:0xf bound_ctrl:1
	v_add_f32_dpp v95, v98, v206 quad_perm:[1,0,3,2] row_mask:0xf bank_mask:0xf bound_ctrl:1
	v_add_f32_dpp v52, v52, v207 quad_perm:[1,0,3,2] row_mask:0xf bank_mask:0xf bound_ctrl:1
	v_xor_b32_e32 v200, v83, v53
	v_xor_b32_e32 v201, v83, v95
	v_xor_b32_e32 v202, v83, v94
	v_xor_b32_e32 v203, v83, v52
	v_add_f32_dpp v204, v53, v200 quad_perm:[2,3,0,1] row_mask:0xf bank_mask:0xf bound_ctrl:1
	v_add_f32_dpp v205, v95, v201 quad_perm:[2,3,0,1] row_mask:0xf bank_mask:0xf bound_ctrl:1
	v_add_f32_dpp v206, v94, v202 quad_perm:[2,3,0,1] row_mask:0xf bank_mask:0xf bound_ctrl:1
	v_add_f32_dpp v207, v52, v203 quad_perm:[2,3,0,1] row_mask:0xf bank_mask:0xf bound_ctrl:1
	v_add_f32_dpp v53, v204, v204 row_shl:4 row_mask:0xf bank_mask:0x5
	v_add_f32_dpp v95, v205, v205 row_shl:4 row_mask:0xf bank_mask:0x5
	v_add_f32_dpp v94, v206, v206 row_shl:4 row_mask:0xf bank_mask:0x5
	v_add_f32_dpp v96, v207, v207 row_shl:4 row_mask:0xf bank_mask:0x5
	v_sub_f32_dpp v53, v204, v204 row_shr:4 row_mask:0xf bank_mask:0xa
	v_sub_f32_dpp v95, v205, v205 row_shr:4 row_mask:0xf bank_mask:0xa
	v_sub_f32_dpp v94, v206, v206 row_shr:4 row_mask:0xf bank_mask:0xa
	v_sub_f32_dpp v96, v207, v207 row_shr:4 row_mask:0xf bank_mask:0xa
	v_max_f32_e64 v52, |v53|, |v95|
	v_max_f32_e64 v98, |v94|, |v96|
	v_max3_f32 v97, v97, v52, v98
	v_cvt_pk_bf16_f32 v52, v53, v95
	v_cvt_pk_bf16_f32 v53, v94, v96
	v_lshlrev_b32_e32 v94, 16, v50
	v_and_b32_e32 v50, 0xffff0000, v50
	v_lshlrev_b32_e32 v95, 16, v51
	v_and_b32_e32 v51, 0xffff0000, v51
	v_add_f32_e32 v96, v94, v50
	v_sub_f32_e32 v50, v94, v50
	v_add_f32_e32 v94, v95, v51
	v_sub_f32_e32 v51, v95, v51
	v_add_f32_e32 v95, v96, v94
	v_sub_f32_e32 v94, v96, v94
	v_add_f32_e32 v98, v50, v51
	v_sub_f32_e32 v50, v50, v51
	v_xor_b32_e32 v204, v82, v95
	v_xor_b32_e32 v205, v82, v94
	v_xor_b32_e32 v206, v82, v98
	v_xor_b32_e32 v207, v82, v50
	v_add_f32_dpp v51, v95, v204 quad_perm:[1,0,3,2] row_mask:0xf bank_mask:0xf bound_ctrl:1
	v_add_f32_dpp v94, v94, v205 quad_perm:[1,0,3,2] row_mask:0xf bank_mask:0xf bound_ctrl:1
	v_add_f32_dpp v95, v98, v206 quad_perm:[1,0,3,2] row_mask:0xf bank_mask:0xf bound_ctrl:1
	v_add_f32_dpp v50, v50, v207 quad_perm:[1,0,3,2] row_mask:0xf bank_mask:0xf bound_ctrl:1
	v_xor_b32_e32 v200, v83, v51
	v_xor_b32_e32 v201, v83, v95
	v_xor_b32_e32 v202, v83, v94
	v_xor_b32_e32 v203, v83, v50
	v_add_f32_dpp v204, v51, v200 quad_perm:[2,3,0,1] row_mask:0xf bank_mask:0xf bound_ctrl:1
	v_add_f32_dpp v205, v95, v201 quad_perm:[2,3,0,1] row_mask:0xf bank_mask:0xf bound_ctrl:1
	v_add_f32_dpp v206, v94, v202 quad_perm:[2,3,0,1] row_mask:0xf bank_mask:0xf bound_ctrl:1
	v_add_f32_dpp v207, v50, v203 quad_perm:[2,3,0,1] row_mask:0xf bank_mask:0xf bound_ctrl:1
	v_add_f32_dpp v51, v204, v204 row_shl:4 row_mask:0xf bank_mask:0x5
	v_add_f32_dpp v95, v205, v205 row_shl:4 row_mask:0xf bank_mask:0x5
	v_add_f32_dpp v94, v206, v206 row_shl:4 row_mask:0xf bank_mask:0x5
	v_add_f32_dpp v96, v207, v207 row_shl:4 row_mask:0xf bank_mask:0x5
	v_sub_f32_dpp v51, v204, v204 row_shr:4 row_mask:0xf bank_mask:0xa
	v_sub_f32_dpp v95, v205, v205 row_shr:4 row_mask:0xf bank_mask:0xa
	v_sub_f32_dpp v94, v206, v206 row_shr:4 row_mask:0xf bank_mask:0xa
	v_sub_f32_dpp v96, v207, v207 row_shr:4 row_mask:0xf bank_mask:0xa
	v_max_f32_e64 v50, |v51|, |v95|
	v_max_f32_e64 v98, |v94|, |v96|
	v_max3_f32 v97, v97, v50, v98
	v_cvt_pk_bf16_f32 v50, v51, v95
	v_cvt_pk_bf16_f32 v51, v94, v96
	v_lshlrev_b32_e32 v94, 16, v48
	v_and_b32_e32 v48, 0xffff0000, v48
	v_lshlrev_b32_e32 v95, 16, v49
	v_and_b32_e32 v49, 0xffff0000, v49
	v_add_f32_e32 v96, v94, v48
	v_sub_f32_e32 v48, v94, v48
	v_add_f32_e32 v94, v95, v49
	v_sub_f32_e32 v49, v95, v49
	v_add_f32_e32 v95, v96, v94
	v_sub_f32_e32 v94, v96, v94
	v_add_f32_e32 v98, v48, v49
	v_sub_f32_e32 v48, v48, v49
	v_xor_b32_e32 v204, v82, v95
	v_xor_b32_e32 v205, v82, v94
	v_xor_b32_e32 v206, v82, v98
	v_xor_b32_e32 v207, v82, v48
	v_add_f32_dpp v49, v95, v204 quad_perm:[1,0,3,2] row_mask:0xf bank_mask:0xf bound_ctrl:1
	v_add_f32_dpp v94, v94, v205 quad_perm:[1,0,3,2] row_mask:0xf bank_mask:0xf bound_ctrl:1
	v_add_f32_dpp v95, v98, v206 quad_perm:[1,0,3,2] row_mask:0xf bank_mask:0xf bound_ctrl:1
	v_add_f32_dpp v48, v48, v207 quad_perm:[1,0,3,2] row_mask:0xf bank_mask:0xf bound_ctrl:1
	v_xor_b32_e32 v200, v83, v49
	v_xor_b32_e32 v201, v83, v95
	v_xor_b32_e32 v202, v83, v94
	v_xor_b32_e32 v203, v83, v48
	v_add_f32_dpp v204, v49, v200 quad_perm:[2,3,0,1] row_mask:0xf bank_mask:0xf bound_ctrl:1
	v_add_f32_dpp v205, v95, v201 quad_perm:[2,3,0,1] row_mask:0xf bank_mask:0xf bound_ctrl:1
	v_add_f32_dpp v206, v94, v202 quad_perm:[2,3,0,1] row_mask:0xf bank_mask:0xf bound_ctrl:1
	v_add_f32_dpp v207, v48, v203 quad_perm:[2,3,0,1] row_mask:0xf bank_mask:0xf bound_ctrl:1
	v_add_f32_dpp v49, v204, v204 row_shl:4 row_mask:0xf bank_mask:0x5
	v_add_f32_dpp v95, v205, v205 row_shl:4 row_mask:0xf bank_mask:0x5
	v_add_f32_dpp v94, v206, v206 row_shl:4 row_mask:0xf bank_mask:0x5
	v_add_f32_dpp v96, v207, v207 row_shl:4 row_mask:0xf bank_mask:0x5
	v_sub_f32_dpp v49, v204, v204 row_shr:4 row_mask:0xf bank_mask:0xa
	v_sub_f32_dpp v95, v205, v205 row_shr:4 row_mask:0xf bank_mask:0xa
	v_sub_f32_dpp v94, v206, v206 row_shr:4 row_mask:0xf bank_mask:0xa
	v_sub_f32_dpp v96, v207, v207 row_shr:4 row_mask:0xf bank_mask:0xa
	v_max_f32_e64 v48, |v49|, |v95|
	v_max_f32_e64 v98, |v94|, |v96|
	v_max3_f32 v97, v97, v48, v98
	v_cvt_pk_bf16_f32 v48, v49, v95
	v_cvt_pk_bf16_f32 v49, v94, v96
	v_lshlrev_b32_e32 v94, 16, v46
	v_and_b32_e32 v46, 0xffff0000, v46
	v_lshlrev_b32_e32 v95, 16, v47
	v_and_b32_e32 v47, 0xffff0000, v47
	v_add_f32_e32 v96, v94, v46
	v_sub_f32_e32 v46, v94, v46
	v_add_f32_e32 v94, v95, v47
	v_sub_f32_e32 v47, v95, v47
	v_add_f32_e32 v95, v96, v94
	v_sub_f32_e32 v94, v96, v94
	v_add_f32_e32 v98, v46, v47
	v_sub_f32_e32 v46, v46, v47
	v_xor_b32_e32 v204, v82, v95
	v_xor_b32_e32 v205, v82, v94
	v_xor_b32_e32 v206, v82, v98
	v_xor_b32_e32 v207, v82, v46
	v_add_f32_dpp v47, v95, v204 quad_perm:[1,0,3,2] row_mask:0xf bank_mask:0xf bound_ctrl:1
	v_add_f32_dpp v94, v94, v205 quad_perm:[1,0,3,2] row_mask:0xf bank_mask:0xf bound_ctrl:1
	v_add_f32_dpp v95, v98, v206 quad_perm:[1,0,3,2] row_mask:0xf bank_mask:0xf bound_ctrl:1
	v_add_f32_dpp v46, v46, v207 quad_perm:[1,0,3,2] row_mask:0xf bank_mask:0xf bound_ctrl:1
	v_xor_b32_e32 v200, v83, v47
	v_xor_b32_e32 v201, v83, v95
	v_xor_b32_e32 v202, v83, v94
	v_xor_b32_e32 v203, v83, v46
	v_add_f32_dpp v204, v47, v200 quad_perm:[2,3,0,1] row_mask:0xf bank_mask:0xf bound_ctrl:1
	v_add_f32_dpp v205, v95, v201 quad_perm:[2,3,0,1] row_mask:0xf bank_mask:0xf bound_ctrl:1
	v_add_f32_dpp v206, v94, v202 quad_perm:[2,3,0,1] row_mask:0xf bank_mask:0xf bound_ctrl:1
	v_add_f32_dpp v207, v46, v203 quad_perm:[2,3,0,1] row_mask:0xf bank_mask:0xf bound_ctrl:1
	v_add_f32_dpp v47, v204, v204 row_shl:4 row_mask:0xf bank_mask:0x5
	v_add_f32_dpp v95, v205, v205 row_shl:4 row_mask:0xf bank_mask:0x5
	v_add_f32_dpp v94, v206, v206 row_shl:4 row_mask:0xf bank_mask:0x5
	v_add_f32_dpp v96, v207, v207 row_shl:4 row_mask:0xf bank_mask:0x5
	v_sub_f32_dpp v47, v204, v204 row_shr:4 row_mask:0xf bank_mask:0xa
	v_sub_f32_dpp v95, v205, v205 row_shr:4 row_mask:0xf bank_mask:0xa
	v_sub_f32_dpp v94, v206, v206 row_shr:4 row_mask:0xf bank_mask:0xa
	v_sub_f32_dpp v96, v207, v207 row_shr:4 row_mask:0xf bank_mask:0xa
	v_max_f32_e64 v46, |v47|, |v95|
	v_max_f32_e64 v98, |v94|, |v96|
	v_max3_f32 v97, v97, v46, v98
	v_cvt_pk_bf16_f32 v46, v47, v95
	v_cvt_pk_bf16_f32 v47, v94, v96
	v_lshlrev_b32_e32 v94, 16, v44
	v_and_b32_e32 v44, 0xffff0000, v44
	v_lshlrev_b32_e32 v95, 16, v45
	v_and_b32_e32 v45, 0xffff0000, v45
	v_add_f32_e32 v96, v94, v44
	v_sub_f32_e32 v44, v94, v44
	v_add_f32_e32 v94, v95, v45
	v_sub_f32_e32 v45, v95, v45
	v_add_f32_e32 v95, v96, v94
	v_sub_f32_e32 v94, v96, v94
	v_add_f32_e32 v98, v44, v45
	v_sub_f32_e32 v44, v44, v45
	v_xor_b32_e32 v204, v82, v95
	v_xor_b32_e32 v205, v82, v94
	v_xor_b32_e32 v206, v82, v98
	v_xor_b32_e32 v207, v82, v44
	v_add_f32_dpp v45, v95, v204 quad_perm:[1,0,3,2] row_mask:0xf bank_mask:0xf bound_ctrl:1
	v_add_f32_dpp v94, v94, v205 quad_perm:[1,0,3,2] row_mask:0xf bank_mask:0xf bound_ctrl:1
	v_add_f32_dpp v95, v98, v206 quad_perm:[1,0,3,2] row_mask:0xf bank_mask:0xf bound_ctrl:1
	v_add_f32_dpp v44, v44, v207 quad_perm:[1,0,3,2] row_mask:0xf bank_mask:0xf bound_ctrl:1
	v_xor_b32_e32 v200, v83, v45
	v_xor_b32_e32 v201, v83, v95
	v_xor_b32_e32 v202, v83, v94
	v_xor_b32_e32 v203, v83, v44
	v_add_f32_dpp v204, v45, v200 quad_perm:[2,3,0,1] row_mask:0xf bank_mask:0xf bound_ctrl:1
	v_add_f32_dpp v205, v95, v201 quad_perm:[2,3,0,1] row_mask:0xf bank_mask:0xf bound_ctrl:1
	v_add_f32_dpp v206, v94, v202 quad_perm:[2,3,0,1] row_mask:0xf bank_mask:0xf bound_ctrl:1
	v_add_f32_dpp v207, v44, v203 quad_perm:[2,3,0,1] row_mask:0xf bank_mask:0xf bound_ctrl:1
	v_add_f32_dpp v45, v204, v204 row_shl:4 row_mask:0xf bank_mask:0x5
	v_add_f32_dpp v95, v205, v205 row_shl:4 row_mask:0xf bank_mask:0x5
	v_add_f32_dpp v94, v206, v206 row_shl:4 row_mask:0xf bank_mask:0x5
	v_add_f32_dpp v96, v207, v207 row_shl:4 row_mask:0xf bank_mask:0x5
	v_sub_f32_dpp v45, v204, v204 row_shr:4 row_mask:0xf bank_mask:0xa
	v_sub_f32_dpp v95, v205, v205 row_shr:4 row_mask:0xf bank_mask:0xa
	v_sub_f32_dpp v94, v206, v206 row_shr:4 row_mask:0xf bank_mask:0xa
	v_sub_f32_dpp v96, v207, v207 row_shr:4 row_mask:0xf bank_mask:0xa
	v_max_f32_e64 v44, |v45|, |v95|
	v_max_f32_e64 v98, |v94|, |v96|
	v_max3_f32 v97, v97, v44, v98
	v_cvt_pk_bf16_f32 v44, v45, v95
	v_cvt_pk_bf16_f32 v45, v94, v96
	v_lshlrev_b32_e32 v94, 16, v42
	v_and_b32_e32 v42, 0xffff0000, v42
	v_lshlrev_b32_e32 v95, 16, v43
	v_and_b32_e32 v43, 0xffff0000, v43
	v_add_f32_e32 v96, v94, v42
	v_sub_f32_e32 v42, v94, v42
	v_add_f32_e32 v94, v95, v43
	v_sub_f32_e32 v43, v95, v43
	v_add_f32_e32 v95, v96, v94
	v_sub_f32_e32 v94, v96, v94
	v_add_f32_e32 v98, v42, v43
	v_sub_f32_e32 v42, v42, v43
	v_xor_b32_e32 v204, v82, v95
	v_xor_b32_e32 v205, v82, v94
	v_xor_b32_e32 v206, v82, v98
	v_xor_b32_e32 v207, v82, v42
	v_add_f32_dpp v43, v95, v204 quad_perm:[1,0,3,2] row_mask:0xf bank_mask:0xf bound_ctrl:1
	v_add_f32_dpp v94, v94, v205 quad_perm:[1,0,3,2] row_mask:0xf bank_mask:0xf bound_ctrl:1
	v_add_f32_dpp v95, v98, v206 quad_perm:[1,0,3,2] row_mask:0xf bank_mask:0xf bound_ctrl:1
	v_add_f32_dpp v42, v42, v207 quad_perm:[1,0,3,2] row_mask:0xf bank_mask:0xf bound_ctrl:1
	v_xor_b32_e32 v200, v83, v43
	v_xor_b32_e32 v201, v83, v95
	v_xor_b32_e32 v202, v83, v94
	v_xor_b32_e32 v203, v83, v42
	v_add_f32_dpp v204, v43, v200 quad_perm:[2,3,0,1] row_mask:0xf bank_mask:0xf bound_ctrl:1
	v_add_f32_dpp v205, v95, v201 quad_perm:[2,3,0,1] row_mask:0xf bank_mask:0xf bound_ctrl:1
	v_add_f32_dpp v206, v94, v202 quad_perm:[2,3,0,1] row_mask:0xf bank_mask:0xf bound_ctrl:1
	v_add_f32_dpp v207, v42, v203 quad_perm:[2,3,0,1] row_mask:0xf bank_mask:0xf bound_ctrl:1
	v_add_f32_dpp v43, v204, v204 row_shl:4 row_mask:0xf bank_mask:0x5
	v_add_f32_dpp v95, v205, v205 row_shl:4 row_mask:0xf bank_mask:0x5
	v_add_f32_dpp v94, v206, v206 row_shl:4 row_mask:0xf bank_mask:0x5
	v_add_f32_dpp v96, v207, v207 row_shl:4 row_mask:0xf bank_mask:0x5
	v_sub_f32_dpp v43, v204, v204 row_shr:4 row_mask:0xf bank_mask:0xa
	v_sub_f32_dpp v95, v205, v205 row_shr:4 row_mask:0xf bank_mask:0xa
	v_sub_f32_dpp v94, v206, v206 row_shr:4 row_mask:0xf bank_mask:0xa
	v_sub_f32_dpp v96, v207, v207 row_shr:4 row_mask:0xf bank_mask:0xa
	v_max_f32_e64 v42, |v43|, |v95|
	v_max_f32_e64 v98, |v94|, |v96|
	v_max3_f32 v97, v97, v42, v98
	v_cvt_pk_bf16_f32 v42, v43, v95
	v_cvt_pk_bf16_f32 v43, v94, v96
	v_lshlrev_b32_e32 v94, 16, v40
	v_and_b32_e32 v40, 0xffff0000, v40
	v_lshlrev_b32_e32 v95, 16, v41
	v_and_b32_e32 v41, 0xffff0000, v41
	v_add_f32_e32 v96, v94, v40
	v_sub_f32_e32 v40, v94, v40
	v_add_f32_e32 v94, v95, v41
	v_sub_f32_e32 v41, v95, v41
	v_add_f32_e32 v95, v96, v94
	v_sub_f32_e32 v94, v96, v94
	v_add_f32_e32 v98, v40, v41
	v_sub_f32_e32 v40, v40, v41
	v_xor_b32_e32 v204, v82, v95
	v_xor_b32_e32 v205, v82, v94
	v_xor_b32_e32 v206, v82, v98
	v_xor_b32_e32 v207, v82, v40
	v_add_f32_dpp v41, v95, v204 quad_perm:[1,0,3,2] row_mask:0xf bank_mask:0xf bound_ctrl:1
	v_add_f32_dpp v94, v94, v205 quad_perm:[1,0,3,2] row_mask:0xf bank_mask:0xf bound_ctrl:1
	v_add_f32_dpp v95, v98, v206 quad_perm:[1,0,3,2] row_mask:0xf bank_mask:0xf bound_ctrl:1
	v_add_f32_dpp v40, v40, v207 quad_perm:[1,0,3,2] row_mask:0xf bank_mask:0xf bound_ctrl:1
	v_xor_b32_e32 v200, v83, v41
	v_xor_b32_e32 v201, v83, v95
	v_xor_b32_e32 v202, v83, v94
	v_xor_b32_e32 v203, v83, v40
	v_add_f32_dpp v204, v41, v200 quad_perm:[2,3,0,1] row_mask:0xf bank_mask:0xf bound_ctrl:1
	v_add_f32_dpp v205, v95, v201 quad_perm:[2,3,0,1] row_mask:0xf bank_mask:0xf bound_ctrl:1
	v_add_f32_dpp v206, v94, v202 quad_perm:[2,3,0,1] row_mask:0xf bank_mask:0xf bound_ctrl:1
	v_add_f32_dpp v207, v40, v203 quad_perm:[2,3,0,1] row_mask:0xf bank_mask:0xf bound_ctrl:1
	v_add_f32_dpp v41, v204, v204 row_shl:4 row_mask:0xf bank_mask:0x5
	v_add_f32_dpp v95, v205, v205 row_shl:4 row_mask:0xf bank_mask:0x5
	v_add_f32_dpp v94, v206, v206 row_shl:4 row_mask:0xf bank_mask:0x5
	v_add_f32_dpp v96, v207, v207 row_shl:4 row_mask:0xf bank_mask:0x5
	v_sub_f32_dpp v41, v204, v204 row_shr:4 row_mask:0xf bank_mask:0xa
	v_sub_f32_dpp v95, v205, v205 row_shr:4 row_mask:0xf bank_mask:0xa
	v_sub_f32_dpp v94, v206, v206 row_shr:4 row_mask:0xf bank_mask:0xa
	v_sub_f32_dpp v96, v207, v207 row_shr:4 row_mask:0xf bank_mask:0xa
	v_max_f32_e64 v40, |v41|, |v95|
	v_max_f32_e64 v98, |v94|, |v96|
	v_max3_f32 v97, v97, v40, v98
	v_cvt_pk_bf16_f32 v40, v41, v95
	v_cvt_pk_bf16_f32 v41, v94, v96
	v_lshlrev_b32_e32 v94, 16, v38
	v_and_b32_e32 v38, 0xffff0000, v38
	v_lshlrev_b32_e32 v95, 16, v39
	v_and_b32_e32 v39, 0xffff0000, v39
	v_add_f32_e32 v96, v94, v38
	v_sub_f32_e32 v38, v94, v38
	v_add_f32_e32 v94, v95, v39
	v_sub_f32_e32 v39, v95, v39
	v_add_f32_e32 v95, v96, v94
	v_sub_f32_e32 v94, v96, v94
	v_add_f32_e32 v98, v38, v39
	v_sub_f32_e32 v38, v38, v39
	v_xor_b32_e32 v204, v82, v95
	v_xor_b32_e32 v205, v82, v94
	v_xor_b32_e32 v206, v82, v98
	v_xor_b32_e32 v207, v82, v38
	v_add_f32_dpp v39, v95, v204 quad_perm:[1,0,3,2] row_mask:0xf bank_mask:0xf bound_ctrl:1
	v_add_f32_dpp v94, v94, v205 quad_perm:[1,0,3,2] row_mask:0xf bank_mask:0xf bound_ctrl:1
	v_add_f32_dpp v95, v98, v206 quad_perm:[1,0,3,2] row_mask:0xf bank_mask:0xf bound_ctrl:1
	v_add_f32_dpp v38, v38, v207 quad_perm:[1,0,3,2] row_mask:0xf bank_mask:0xf bound_ctrl:1
	v_xor_b32_e32 v200, v83, v39
	v_xor_b32_e32 v201, v83, v95
	v_xor_b32_e32 v202, v83, v94
	v_xor_b32_e32 v203, v83, v38
	v_add_f32_dpp v204, v39, v200 quad_perm:[2,3,0,1] row_mask:0xf bank_mask:0xf bound_ctrl:1
	v_add_f32_dpp v205, v95, v201 quad_perm:[2,3,0,1] row_mask:0xf bank_mask:0xf bound_ctrl:1
	v_add_f32_dpp v206, v94, v202 quad_perm:[2,3,0,1] row_mask:0xf bank_mask:0xf bound_ctrl:1
	v_add_f32_dpp v207, v38, v203 quad_perm:[2,3,0,1] row_mask:0xf bank_mask:0xf bound_ctrl:1
	v_add_f32_dpp v39, v204, v204 row_shl:4 row_mask:0xf bank_mask:0x5
	v_add_f32_dpp v95, v205, v205 row_shl:4 row_mask:0xf bank_mask:0x5
	v_add_f32_dpp v94, v206, v206 row_shl:4 row_mask:0xf bank_mask:0x5
	v_add_f32_dpp v96, v207, v207 row_shl:4 row_mask:0xf bank_mask:0x5
	v_sub_f32_dpp v39, v204, v204 row_shr:4 row_mask:0xf bank_mask:0xa
	v_sub_f32_dpp v95, v205, v205 row_shr:4 row_mask:0xf bank_mask:0xa
	v_sub_f32_dpp v94, v206, v206 row_shr:4 row_mask:0xf bank_mask:0xa
	v_sub_f32_dpp v96, v207, v207 row_shr:4 row_mask:0xf bank_mask:0xa
	v_max_f32_e64 v38, |v39|, |v95|
	v_max_f32_e64 v98, |v94|, |v96|
	v_max3_f32 v97, v97, v38, v98
	v_cvt_pk_bf16_f32 v38, v39, v95
	v_cvt_pk_bf16_f32 v39, v94, v96
	v_lshlrev_b32_e32 v94, 16, v36
	v_and_b32_e32 v36, 0xffff0000, v36
	v_lshlrev_b32_e32 v95, 16, v37
	v_and_b32_e32 v37, 0xffff0000, v37
	v_add_f32_e32 v96, v94, v36
	v_sub_f32_e32 v36, v94, v36
	v_add_f32_e32 v94, v95, v37
	v_sub_f32_e32 v37, v95, v37
	v_add_f32_e32 v95, v96, v94
	v_sub_f32_e32 v94, v96, v94
	v_add_f32_e32 v98, v36, v37
	v_sub_f32_e32 v36, v36, v37
	v_xor_b32_e32 v204, v82, v95
	v_xor_b32_e32 v205, v82, v94
	v_xor_b32_e32 v206, v82, v98
	v_xor_b32_e32 v207, v82, v36
	v_add_f32_dpp v37, v95, v204 quad_perm:[1,0,3,2] row_mask:0xf bank_mask:0xf bound_ctrl:1
	v_add_f32_dpp v94, v94, v205 quad_perm:[1,0,3,2] row_mask:0xf bank_mask:0xf bound_ctrl:1
	v_add_f32_dpp v95, v98, v206 quad_perm:[1,0,3,2] row_mask:0xf bank_mask:0xf bound_ctrl:1
	v_add_f32_dpp v36, v36, v207 quad_perm:[1,0,3,2] row_mask:0xf bank_mask:0xf bound_ctrl:1
	v_xor_b32_e32 v200, v83, v37
	v_xor_b32_e32 v201, v83, v95
	v_xor_b32_e32 v202, v83, v94
	v_xor_b32_e32 v203, v83, v36
	v_add_f32_dpp v204, v37, v200 quad_perm:[2,3,0,1] row_mask:0xf bank_mask:0xf bound_ctrl:1
	v_add_f32_dpp v205, v95, v201 quad_perm:[2,3,0,1] row_mask:0xf bank_mask:0xf bound_ctrl:1
	v_add_f32_dpp v206, v94, v202 quad_perm:[2,3,0,1] row_mask:0xf bank_mask:0xf bound_ctrl:1
	v_add_f32_dpp v207, v36, v203 quad_perm:[2,3,0,1] row_mask:0xf bank_mask:0xf bound_ctrl:1
	v_add_f32_dpp v37, v204, v204 row_shl:4 row_mask:0xf bank_mask:0x5
	v_add_f32_dpp v95, v205, v205 row_shl:4 row_mask:0xf bank_mask:0x5
	v_add_f32_dpp v94, v206, v206 row_shl:4 row_mask:0xf bank_mask:0x5
	v_add_f32_dpp v96, v207, v207 row_shl:4 row_mask:0xf bank_mask:0x5
	v_sub_f32_dpp v37, v204, v204 row_shr:4 row_mask:0xf bank_mask:0xa
	v_sub_f32_dpp v95, v205, v205 row_shr:4 row_mask:0xf bank_mask:0xa
	v_sub_f32_dpp v94, v206, v206 row_shr:4 row_mask:0xf bank_mask:0xa
	v_sub_f32_dpp v96, v207, v207 row_shr:4 row_mask:0xf bank_mask:0xa
	v_max_f32_e64 v36, |v37|, |v95|
	v_max_f32_e64 v98, |v94|, |v96|
	v_max3_f32 v97, v97, v36, v98
	v_cvt_pk_bf16_f32 v36, v37, v95
	v_cvt_pk_bf16_f32 v37, v94, v96
	v_lshlrev_b32_e32 v94, 16, v34
	v_and_b32_e32 v34, 0xffff0000, v34
	v_lshlrev_b32_e32 v95, 16, v35
	v_and_b32_e32 v35, 0xffff0000, v35
	v_add_f32_e32 v96, v94, v34
	v_sub_f32_e32 v34, v94, v34
	v_add_f32_e32 v94, v95, v35
	v_sub_f32_e32 v35, v95, v35
	v_add_f32_e32 v95, v96, v94
	v_sub_f32_e32 v94, v96, v94
	v_add_f32_e32 v98, v34, v35
	v_sub_f32_e32 v34, v34, v35
	v_xor_b32_e32 v204, v82, v95
	v_xor_b32_e32 v205, v82, v94
	v_xor_b32_e32 v206, v82, v98
	v_xor_b32_e32 v207, v82, v34
	v_add_f32_dpp v35, v95, v204 quad_perm:[1,0,3,2] row_mask:0xf bank_mask:0xf bound_ctrl:1
	v_add_f32_dpp v94, v94, v205 quad_perm:[1,0,3,2] row_mask:0xf bank_mask:0xf bound_ctrl:1
	v_add_f32_dpp v95, v98, v206 quad_perm:[1,0,3,2] row_mask:0xf bank_mask:0xf bound_ctrl:1
	v_add_f32_dpp v34, v34, v207 quad_perm:[1,0,3,2] row_mask:0xf bank_mask:0xf bound_ctrl:1
	v_xor_b32_e32 v200, v83, v35
	v_xor_b32_e32 v201, v83, v95
	v_xor_b32_e32 v202, v83, v94
	v_xor_b32_e32 v203, v83, v34
	v_add_f32_dpp v204, v35, v200 quad_perm:[2,3,0,1] row_mask:0xf bank_mask:0xf bound_ctrl:1
	v_add_f32_dpp v205, v95, v201 quad_perm:[2,3,0,1] row_mask:0xf bank_mask:0xf bound_ctrl:1
	v_add_f32_dpp v206, v94, v202 quad_perm:[2,3,0,1] row_mask:0xf bank_mask:0xf bound_ctrl:1
	v_add_f32_dpp v207, v34, v203 quad_perm:[2,3,0,1] row_mask:0xf bank_mask:0xf bound_ctrl:1
	v_add_f32_dpp v35, v204, v204 row_shl:4 row_mask:0xf bank_mask:0x5
	v_add_f32_dpp v95, v205, v205 row_shl:4 row_mask:0xf bank_mask:0x5
	v_add_f32_dpp v94, v206, v206 row_shl:4 row_mask:0xf bank_mask:0x5
	v_add_f32_dpp v96, v207, v207 row_shl:4 row_mask:0xf bank_mask:0x5
	v_sub_f32_dpp v35, v204, v204 row_shr:4 row_mask:0xf bank_mask:0xa
	v_sub_f32_dpp v95, v205, v205 row_shr:4 row_mask:0xf bank_mask:0xa
	v_sub_f32_dpp v94, v206, v206 row_shr:4 row_mask:0xf bank_mask:0xa
	v_sub_f32_dpp v96, v207, v207 row_shr:4 row_mask:0xf bank_mask:0xa
	v_max_f32_e64 v34, |v35|, |v95|
	v_max_f32_e64 v98, |v94|, |v96|
	v_max3_f32 v97, v97, v34, v98
	v_cvt_pk_bf16_f32 v34, v35, v95
	v_cvt_pk_bf16_f32 v35, v94, v96
	v_lshlrev_b32_e32 v94, 16, v32
	v_and_b32_e32 v32, 0xffff0000, v32
	v_lshlrev_b32_e32 v95, 16, v33
	v_and_b32_e32 v33, 0xffff0000, v33
	v_add_f32_e32 v96, v94, v32
	v_sub_f32_e32 v32, v94, v32
	v_add_f32_e32 v94, v95, v33
	v_sub_f32_e32 v33, v95, v33
	v_add_f32_e32 v95, v96, v94
	v_sub_f32_e32 v94, v96, v94
	v_add_f32_e32 v98, v32, v33
	v_sub_f32_e32 v32, v32, v33
	v_xor_b32_e32 v204, v82, v95
	v_xor_b32_e32 v205, v82, v94
	v_xor_b32_e32 v206, v82, v98
	v_xor_b32_e32 v207, v82, v32
	v_add_f32_dpp v33, v95, v204 quad_perm:[1,0,3,2] row_mask:0xf bank_mask:0xf bound_ctrl:1
	v_add_f32_dpp v94, v94, v205 quad_perm:[1,0,3,2] row_mask:0xf bank_mask:0xf bound_ctrl:1
	v_add_f32_dpp v95, v98, v206 quad_perm:[1,0,3,2] row_mask:0xf bank_mask:0xf bound_ctrl:1
	v_add_f32_dpp v32, v32, v207 quad_perm:[1,0,3,2] row_mask:0xf bank_mask:0xf bound_ctrl:1
	v_xor_b32_e32 v200, v83, v33
	v_xor_b32_e32 v201, v83, v95
	v_xor_b32_e32 v202, v83, v94
	v_xor_b32_e32 v203, v83, v32
	v_add_f32_dpp v204, v33, v200 quad_perm:[2,3,0,1] row_mask:0xf bank_mask:0xf bound_ctrl:1
	v_add_f32_dpp v205, v95, v201 quad_perm:[2,3,0,1] row_mask:0xf bank_mask:0xf bound_ctrl:1
	v_add_f32_dpp v206, v94, v202 quad_perm:[2,3,0,1] row_mask:0xf bank_mask:0xf bound_ctrl:1
	v_add_f32_dpp v207, v32, v203 quad_perm:[2,3,0,1] row_mask:0xf bank_mask:0xf bound_ctrl:1
	v_add_f32_dpp v33, v204, v204 row_shl:4 row_mask:0xf bank_mask:0x5
	v_add_f32_dpp v95, v205, v205 row_shl:4 row_mask:0xf bank_mask:0x5
	v_add_f32_dpp v94, v206, v206 row_shl:4 row_mask:0xf bank_mask:0x5
	v_add_f32_dpp v96, v207, v207 row_shl:4 row_mask:0xf bank_mask:0x5
	v_sub_f32_dpp v33, v204, v204 row_shr:4 row_mask:0xf bank_mask:0xa
	v_sub_f32_dpp v95, v205, v205 row_shr:4 row_mask:0xf bank_mask:0xa
	v_sub_f32_dpp v94, v206, v206 row_shr:4 row_mask:0xf bank_mask:0xa
	v_sub_f32_dpp v96, v207, v207 row_shr:4 row_mask:0xf bank_mask:0xa
	v_max_f32_e64 v32, |v33|, |v95|
	v_max_f32_e64 v98, |v94|, |v96|
	v_max3_f32 v97, v97, v32, v98
	v_cvt_pk_bf16_f32 v32, v33, v95
	v_cvt_pk_bf16_f32 v33, v94, v96
	v_lshlrev_b32_e32 v94, 16, v30
	v_and_b32_e32 v30, 0xffff0000, v30
	v_lshlrev_b32_e32 v95, 16, v31
	v_and_b32_e32 v31, 0xffff0000, v31
	v_add_f32_e32 v96, v94, v30
	v_sub_f32_e32 v30, v94, v30
	v_add_f32_e32 v94, v95, v31
	v_sub_f32_e32 v31, v95, v31
	v_add_f32_e32 v95, v96, v94
	v_sub_f32_e32 v94, v96, v94
	v_add_f32_e32 v98, v30, v31
	v_sub_f32_e32 v30, v30, v31
	v_xor_b32_e32 v204, v82, v95
	v_xor_b32_e32 v205, v82, v94
	v_xor_b32_e32 v206, v82, v98
	v_xor_b32_e32 v207, v82, v30
	v_add_f32_dpp v31, v95, v204 quad_perm:[1,0,3,2] row_mask:0xf bank_mask:0xf bound_ctrl:1
	v_add_f32_dpp v94, v94, v205 quad_perm:[1,0,3,2] row_mask:0xf bank_mask:0xf bound_ctrl:1
	v_add_f32_dpp v95, v98, v206 quad_perm:[1,0,3,2] row_mask:0xf bank_mask:0xf bound_ctrl:1
	v_add_f32_dpp v30, v30, v207 quad_perm:[1,0,3,2] row_mask:0xf bank_mask:0xf bound_ctrl:1
	v_xor_b32_e32 v200, v83, v31
	v_xor_b32_e32 v201, v83, v95
	v_xor_b32_e32 v202, v83, v94
	v_xor_b32_e32 v203, v83, v30
	v_add_f32_dpp v204, v31, v200 quad_perm:[2,3,0,1] row_mask:0xf bank_mask:0xf bound_ctrl:1
	v_add_f32_dpp v205, v95, v201 quad_perm:[2,3,0,1] row_mask:0xf bank_mask:0xf bound_ctrl:1
	v_add_f32_dpp v206, v94, v202 quad_perm:[2,3,0,1] row_mask:0xf bank_mask:0xf bound_ctrl:1
	v_add_f32_dpp v207, v30, v203 quad_perm:[2,3,0,1] row_mask:0xf bank_mask:0xf bound_ctrl:1
	v_add_f32_dpp v31, v204, v204 row_shl:4 row_mask:0xf bank_mask:0x5
	v_add_f32_dpp v95, v205, v205 row_shl:4 row_mask:0xf bank_mask:0x5
	v_add_f32_dpp v94, v206, v206 row_shl:4 row_mask:0xf bank_mask:0x5
	v_add_f32_dpp v96, v207, v207 row_shl:4 row_mask:0xf bank_mask:0x5
	v_sub_f32_dpp v31, v204, v204 row_shr:4 row_mask:0xf bank_mask:0xa
	v_sub_f32_dpp v95, v205, v205 row_shr:4 row_mask:0xf bank_mask:0xa
	v_sub_f32_dpp v94, v206, v206 row_shr:4 row_mask:0xf bank_mask:0xa
	v_sub_f32_dpp v96, v207, v207 row_shr:4 row_mask:0xf bank_mask:0xa
	v_max_f32_e64 v30, |v31|, |v95|
	v_max_f32_e64 v98, |v94|, |v96|
	v_max3_f32 v97, v97, v30, v98
	v_cvt_pk_bf16_f32 v30, v31, v95
	v_cvt_pk_bf16_f32 v31, v94, v96
	v_lshlrev_b32_e32 v94, 16, v28
	v_and_b32_e32 v28, 0xffff0000, v28
	v_lshlrev_b32_e32 v95, 16, v29
	v_and_b32_e32 v29, 0xffff0000, v29
	v_add_f32_e32 v96, v94, v28
	v_sub_f32_e32 v28, v94, v28
	v_add_f32_e32 v94, v95, v29
	v_sub_f32_e32 v29, v95, v29
	v_add_f32_e32 v95, v96, v94
	v_sub_f32_e32 v94, v96, v94
	v_add_f32_e32 v98, v28, v29
	v_sub_f32_e32 v28, v28, v29
	v_xor_b32_e32 v204, v82, v95
	v_xor_b32_e32 v205, v82, v94
	v_xor_b32_e32 v206, v82, v98
	v_xor_b32_e32 v207, v82, v28
	v_add_f32_dpp v29, v95, v204 quad_perm:[1,0,3,2] row_mask:0xf bank_mask:0xf bound_ctrl:1
	v_add_f32_dpp v94, v94, v205 quad_perm:[1,0,3,2] row_mask:0xf bank_mask:0xf bound_ctrl:1
	v_add_f32_dpp v95, v98, v206 quad_perm:[1,0,3,2] row_mask:0xf bank_mask:0xf bound_ctrl:1
	v_add_f32_dpp v28, v28, v207 quad_perm:[1,0,3,2] row_mask:0xf bank_mask:0xf bound_ctrl:1
	v_xor_b32_e32 v200, v83, v29
	v_xor_b32_e32 v201, v83, v95
	v_xor_b32_e32 v202, v83, v94
	v_xor_b32_e32 v203, v83, v28
	v_add_f32_dpp v204, v29, v200 quad_perm:[2,3,0,1] row_mask:0xf bank_mask:0xf bound_ctrl:1
	v_add_f32_dpp v205, v95, v201 quad_perm:[2,3,0,1] row_mask:0xf bank_mask:0xf bound_ctrl:1
	v_add_f32_dpp v206, v94, v202 quad_perm:[2,3,0,1] row_mask:0xf bank_mask:0xf bound_ctrl:1
	v_add_f32_dpp v207, v28, v203 quad_perm:[2,3,0,1] row_mask:0xf bank_mask:0xf bound_ctrl:1
	v_add_f32_dpp v29, v204, v204 row_shl:4 row_mask:0xf bank_mask:0x5
	v_add_f32_dpp v95, v205, v205 row_shl:4 row_mask:0xf bank_mask:0x5
	v_add_f32_dpp v94, v206, v206 row_shl:4 row_mask:0xf bank_mask:0x5
	v_add_f32_dpp v96, v207, v207 row_shl:4 row_mask:0xf bank_mask:0x5
	v_sub_f32_dpp v29, v204, v204 row_shr:4 row_mask:0xf bank_mask:0xa
	v_sub_f32_dpp v95, v205, v205 row_shr:4 row_mask:0xf bank_mask:0xa
	v_sub_f32_dpp v94, v206, v206 row_shr:4 row_mask:0xf bank_mask:0xa
	v_sub_f32_dpp v96, v207, v207 row_shr:4 row_mask:0xf bank_mask:0xa
	v_max_f32_e64 v28, |v29|, |v95|
	v_max_f32_e64 v98, |v94|, |v96|
	v_max3_f32 v97, v97, v28, v98
	v_cvt_pk_bf16_f32 v28, v29, v95
	v_cvt_pk_bf16_f32 v29, v94, v96
	v_lshlrev_b32_e32 v94, 16, v26
	v_and_b32_e32 v26, 0xffff0000, v26
	v_lshlrev_b32_e32 v95, 16, v27
	v_and_b32_e32 v27, 0xffff0000, v27
	v_add_f32_e32 v96, v94, v26
	v_sub_f32_e32 v26, v94, v26
	v_add_f32_e32 v94, v95, v27
	v_sub_f32_e32 v27, v95, v27
	v_add_f32_e32 v95, v96, v94
	v_sub_f32_e32 v94, v96, v94
	v_add_f32_e32 v98, v26, v27
	v_sub_f32_e32 v26, v26, v27
	v_xor_b32_e32 v204, v82, v95
	v_xor_b32_e32 v205, v82, v94
	v_xor_b32_e32 v206, v82, v98
	v_xor_b32_e32 v207, v82, v26
	v_add_f32_dpp v27, v95, v204 quad_perm:[1,0,3,2] row_mask:0xf bank_mask:0xf bound_ctrl:1
	v_add_f32_dpp v94, v94, v205 quad_perm:[1,0,3,2] row_mask:0xf bank_mask:0xf bound_ctrl:1
	v_add_f32_dpp v95, v98, v206 quad_perm:[1,0,3,2] row_mask:0xf bank_mask:0xf bound_ctrl:1
	v_add_f32_dpp v26, v26, v207 quad_perm:[1,0,3,2] row_mask:0xf bank_mask:0xf bound_ctrl:1
	v_xor_b32_e32 v200, v83, v27
	v_xor_b32_e32 v201, v83, v95
	v_xor_b32_e32 v202, v83, v94
	v_xor_b32_e32 v203, v83, v26
	v_add_f32_dpp v204, v27, v200 quad_perm:[2,3,0,1] row_mask:0xf bank_mask:0xf bound_ctrl:1
	v_add_f32_dpp v205, v95, v201 quad_perm:[2,3,0,1] row_mask:0xf bank_mask:0xf bound_ctrl:1
	v_add_f32_dpp v206, v94, v202 quad_perm:[2,3,0,1] row_mask:0xf bank_mask:0xf bound_ctrl:1
	v_add_f32_dpp v207, v26, v203 quad_perm:[2,3,0,1] row_mask:0xf bank_mask:0xf bound_ctrl:1
	v_add_f32_dpp v27, v204, v204 row_shl:4 row_mask:0xf bank_mask:0x5
	v_add_f32_dpp v95, v205, v205 row_shl:4 row_mask:0xf bank_mask:0x5
	v_add_f32_dpp v94, v206, v206 row_shl:4 row_mask:0xf bank_mask:0x5
	v_add_f32_dpp v96, v207, v207 row_shl:4 row_mask:0xf bank_mask:0x5
	v_sub_f32_dpp v27, v204, v204 row_shr:4 row_mask:0xf bank_mask:0xa
	v_sub_f32_dpp v95, v205, v205 row_shr:4 row_mask:0xf bank_mask:0xa
	v_sub_f32_dpp v94, v206, v206 row_shr:4 row_mask:0xf bank_mask:0xa
	v_sub_f32_dpp v96, v207, v207 row_shr:4 row_mask:0xf bank_mask:0xa
	v_max_f32_e64 v26, |v27|, |v95|
	v_max_f32_e64 v98, |v94|, |v96|
	v_max3_f32 v97, v97, v26, v98
	v_cvt_pk_bf16_f32 v26, v27, v95
	v_cvt_pk_bf16_f32 v27, v94, v96
	v_lshlrev_b32_e32 v94, 16, v24
	v_and_b32_e32 v24, 0xffff0000, v24
	v_lshlrev_b32_e32 v95, 16, v25
	v_and_b32_e32 v25, 0xffff0000, v25
	v_add_f32_e32 v96, v94, v24
	v_sub_f32_e32 v24, v94, v24
	v_add_f32_e32 v94, v95, v25
	v_sub_f32_e32 v25, v95, v25
	v_add_f32_e32 v95, v96, v94
	v_sub_f32_e32 v94, v96, v94
	v_add_f32_e32 v98, v24, v25
	v_sub_f32_e32 v24, v24, v25
	v_xor_b32_e32 v204, v82, v95
	v_xor_b32_e32 v205, v82, v94
	v_xor_b32_e32 v206, v82, v98
	v_xor_b32_e32 v207, v82, v24
	v_add_f32_dpp v25, v95, v204 quad_perm:[1,0,3,2] row_mask:0xf bank_mask:0xf bound_ctrl:1
	v_add_f32_dpp v94, v94, v205 quad_perm:[1,0,3,2] row_mask:0xf bank_mask:0xf bound_ctrl:1
	v_add_f32_dpp v95, v98, v206 quad_perm:[1,0,3,2] row_mask:0xf bank_mask:0xf bound_ctrl:1
	v_add_f32_dpp v24, v24, v207 quad_perm:[1,0,3,2] row_mask:0xf bank_mask:0xf bound_ctrl:1
	v_xor_b32_e32 v200, v83, v25
	v_xor_b32_e32 v201, v83, v95
	v_xor_b32_e32 v202, v83, v94
	v_xor_b32_e32 v203, v83, v24
	v_add_f32_dpp v204, v25, v200 quad_perm:[2,3,0,1] row_mask:0xf bank_mask:0xf bound_ctrl:1
	v_add_f32_dpp v205, v95, v201 quad_perm:[2,3,0,1] row_mask:0xf bank_mask:0xf bound_ctrl:1
	v_add_f32_dpp v206, v94, v202 quad_perm:[2,3,0,1] row_mask:0xf bank_mask:0xf bound_ctrl:1
	v_add_f32_dpp v207, v24, v203 quad_perm:[2,3,0,1] row_mask:0xf bank_mask:0xf bound_ctrl:1
	v_add_f32_dpp v24, v204, v204 row_shl:4 row_mask:0xf bank_mask:0x5
	v_add_f32_dpp v25, v205, v205 row_shl:4 row_mask:0xf bank_mask:0x5
	v_add_f32_dpp v94, v206, v206 row_shl:4 row_mask:0xf bank_mask:0x5
	v_add_f32_dpp v95, v207, v207 row_shl:4 row_mask:0xf bank_mask:0x5
	v_sub_f32_dpp v24, v204, v204 row_shr:4 row_mask:0xf bank_mask:0xa
	v_sub_f32_dpp v25, v205, v205 row_shr:4 row_mask:0xf bank_mask:0xa
	v_sub_f32_dpp v94, v206, v206 row_shr:4 row_mask:0xf bank_mask:0xa
	v_sub_f32_dpp v95, v207, v207 row_shr:4 row_mask:0xf bank_mask:0xa
	v_max_f32_e64 v96, |v24|, |v25|
	v_max_f32_e64 v98, |v94|, |v95|
	v_max3_f32 v98, v97, v96, v98
	v_lshlrev_b32_e32 v96, 16, v22
	v_and_b32_e32 v22, 0xffff0000, v22
	v_lshlrev_b32_e32 v97, 16, v23
	v_and_b32_e32 v23, 0xffff0000, v23
	v_add_f32_e32 v99, v96, v22
	v_sub_f32_e32 v22, v96, v22
	v_add_f32_e32 v96, v97, v23
	v_sub_f32_e32 v23, v97, v23
	v_add_f32_e32 v97, v99, v96
	v_sub_f32_e32 v96, v99, v96
	v_add_f32_e32 v100, v22, v23
	v_sub_f32_e32 v22, v22, v23
	v_xor_b32_e32 v204, v82, v97
	v_xor_b32_e32 v205, v82, v96
	v_xor_b32_e32 v206, v82, v100
	v_xor_b32_e32 v207, v82, v22
	v_cvt_pk_bf16_f32 v24, v24, v25
	v_cvt_pk_bf16_f32 v25, v94, v95
	v_add_f32_dpp v23, v97, v204 quad_perm:[1,0,3,2] row_mask:0xf bank_mask:0xf bound_ctrl:1
	v_add_f32_dpp v96, v96, v205 quad_perm:[1,0,3,2] row_mask:0xf bank_mask:0xf bound_ctrl:1
	v_add_f32_dpp v97, v100, v206 quad_perm:[1,0,3,2] row_mask:0xf bank_mask:0xf bound_ctrl:1
	v_add_f32_dpp v22, v22, v207 quad_perm:[1,0,3,2] row_mask:0xf bank_mask:0xf bound_ctrl:1
	v_xor_b32_e32 v200, v83, v23
	v_xor_b32_e32 v201, v83, v97
	v_xor_b32_e32 v202, v83, v96
	v_xor_b32_e32 v203, v83, v22
	v_add_f32_dpp v204, v23, v200 quad_perm:[2,3,0,1] row_mask:0xf bank_mask:0xf bound_ctrl:1
	v_add_f32_dpp v205, v97, v201 quad_perm:[2,3,0,1] row_mask:0xf bank_mask:0xf bound_ctrl:1
	v_add_f32_dpp v206, v96, v202 quad_perm:[2,3,0,1] row_mask:0xf bank_mask:0xf bound_ctrl:1
	v_add_f32_dpp v207, v22, v203 quad_perm:[2,3,0,1] row_mask:0xf bank_mask:0xf bound_ctrl:1
	v_add_f32_dpp v22, v204, v204 row_shl:4 row_mask:0xf bank_mask:0x5
	v_add_f32_dpp v23, v205, v205 row_shl:4 row_mask:0xf bank_mask:0x5
	v_add_f32_dpp v96, v206, v206 row_shl:4 row_mask:0xf bank_mask:0x5
	v_add_f32_dpp v97, v207, v207 row_shl:4 row_mask:0xf bank_mask:0x5
	v_sub_f32_dpp v22, v204, v204 row_shr:4 row_mask:0xf bank_mask:0xa
	v_sub_f32_dpp v23, v205, v205 row_shr:4 row_mask:0xf bank_mask:0xa
	v_sub_f32_dpp v96, v206, v206 row_shr:4 row_mask:0xf bank_mask:0xa
	v_sub_f32_dpp v97, v207, v207 row_shr:4 row_mask:0xf bank_mask:0xa
	v_max_f32_e64 v99, |v22|, |v23|
	v_max_f32_e64 v100, |v96|, |v97|
	v_max3_f32 v98, v98, v99, v100
	v_lshlrev_b32_e32 v99, 16, v20
	v_and_b32_e32 v20, 0xffff0000, v20
	v_lshlrev_b32_e32 v100, 16, v21
	v_and_b32_e32 v21, 0xffff0000, v21
	v_add_f32_e32 v101, v99, v20
	v_sub_f32_e32 v20, v99, v20
	v_add_f32_e32 v99, v100, v21
	v_sub_f32_e32 v21, v100, v21
	v_add_f32_e32 v100, v101, v99
	v_sub_f32_e32 v99, v101, v99
	v_add_f32_e32 v102, v20, v21
	v_sub_f32_e32 v20, v20, v21
	v_xor_b32_e32 v204, v82, v100
	v_xor_b32_e32 v205, v82, v99
	v_xor_b32_e32 v206, v82, v102
	v_xor_b32_e32 v207, v82, v20
	v_cvt_pk_bf16_f32 v22, v22, v23
	v_cvt_pk_bf16_f32 v23, v96, v97
	v_add_f32_dpp v21, v100, v204 quad_perm:[1,0,3,2] row_mask:0xf bank_mask:0xf bound_ctrl:1
	v_add_f32_dpp v99, v99, v205 quad_perm:[1,0,3,2] row_mask:0xf bank_mask:0xf bound_ctrl:1
	v_add_f32_dpp v100, v102, v206 quad_perm:[1,0,3,2] row_mask:0xf bank_mask:0xf bound_ctrl:1
	v_add_f32_dpp v20, v20, v207 quad_perm:[1,0,3,2] row_mask:0xf bank_mask:0xf bound_ctrl:1
	v_xor_b32_e32 v200, v83, v21
	v_xor_b32_e32 v201, v83, v100
	v_xor_b32_e32 v202, v83, v99
	v_xor_b32_e32 v203, v83, v20
	v_add_f32_dpp v204, v21, v200 quad_perm:[2,3,0,1] row_mask:0xf bank_mask:0xf bound_ctrl:1
	v_add_f32_dpp v205, v100, v201 quad_perm:[2,3,0,1] row_mask:0xf bank_mask:0xf bound_ctrl:1
	v_add_f32_dpp v206, v99, v202 quad_perm:[2,3,0,1] row_mask:0xf bank_mask:0xf bound_ctrl:1
	v_add_f32_dpp v207, v20, v203 quad_perm:[2,3,0,1] row_mask:0xf bank_mask:0xf bound_ctrl:1
	v_add_f32_dpp v21, v204, v204 row_shl:4 row_mask:0xf bank_mask:0x5
	v_add_f32_dpp v100, v205, v205 row_shl:4 row_mask:0xf bank_mask:0x5
	v_add_f32_dpp v99, v206, v206 row_shl:4 row_mask:0xf bank_mask:0x5
	v_add_f32_dpp v20, v207, v207 row_shl:4 row_mask:0xf bank_mask:0x5
	v_sub_f32_dpp v21, v204, v204 row_shr:4 row_mask:0xf bank_mask:0xa
	v_sub_f32_dpp v100, v205, v205 row_shr:4 row_mask:0xf bank_mask:0xa
	v_sub_f32_dpp v99, v206, v206 row_shr:4 row_mask:0xf bank_mask:0xa
	v_sub_f32_dpp v20, v207, v207 row_shr:4 row_mask:0xf bank_mask:0xa
	v_cvt_pk_bf16_f32 v96, v21, v100
	v_max_f32_e64 v101, |v21|, |v100|
	v_max_f32_e64 v102, |v99|, |v20|
	v_max3_f32 v98, v98, v101, v102
	v_lshlrev_b32_e32 v101, 16, v18
	v_and_b32_e32 v18, 0xffff0000, v18
	v_lshlrev_b32_e32 v102, 16, v19
	v_and_b32_e32 v19, 0xffff0000, v19
	v_add_f32_e32 v103, v101, v18
	v_sub_f32_e32 v18, v101, v18
	v_add_f32_e32 v101, v102, v19
	v_sub_f32_e32 v19, v102, v19
	v_add_f32_e32 v102, v103, v101
	v_sub_f32_e32 v101, v103, v101
	v_add_f32_e32 v104, v18, v19
	v_sub_f32_e32 v18, v18, v19
	v_xor_b32_e32 v204, v82, v102
	v_xor_b32_e32 v205, v82, v101
	v_xor_b32_e32 v206, v82, v104
	v_xor_b32_e32 v207, v82, v18
	v_cvt_pk_bf16_f32 v97, v99, v20
	v_add_f32_dpp v19, v102, v204 quad_perm:[1,0,3,2] row_mask:0xf bank_mask:0xf bound_ctrl:1
	v_add_f32_dpp v101, v101, v205 quad_perm:[1,0,3,2] row_mask:0xf bank_mask:0xf bound_ctrl:1
	v_add_f32_dpp v102, v104, v206 quad_perm:[1,0,3,2] row_mask:0xf bank_mask:0xf bound_ctrl:1
	v_add_f32_dpp v18, v18, v207 quad_perm:[1,0,3,2] row_mask:0xf bank_mask:0xf bound_ctrl:1
	v_xor_b32_e32 v200, v83, v19
	v_xor_b32_e32 v201, v83, v102
	v_xor_b32_e32 v202, v83, v101
	v_xor_b32_e32 v203, v83, v18
	v_add_f32_dpp v204, v19, v200 quad_perm:[2,3,0,1] row_mask:0xf bank_mask:0xf bound_ctrl:1
	v_add_f32_dpp v205, v102, v201 quad_perm:[2,3,0,1] row_mask:0xf bank_mask:0xf bound_ctrl:1
	v_add_f32_dpp v206, v101, v202 quad_perm:[2,3,0,1] row_mask:0xf bank_mask:0xf bound_ctrl:1
	v_add_f32_dpp v207, v18, v203 quad_perm:[2,3,0,1] row_mask:0xf bank_mask:0xf bound_ctrl:1
	v_add_f32_dpp v19, v204, v204 row_shl:4 row_mask:0xf bank_mask:0x5
	v_add_f32_dpp v102, v205, v205 row_shl:4 row_mask:0xf bank_mask:0x5
	v_add_f32_dpp v101, v206, v206 row_shl:4 row_mask:0xf bank_mask:0x5
	v_add_f32_dpp v18, v207, v207 row_shl:4 row_mask:0xf bank_mask:0x5
	v_sub_f32_dpp v19, v204, v204 row_shr:4 row_mask:0xf bank_mask:0xa
	v_sub_f32_dpp v102, v205, v205 row_shr:4 row_mask:0xf bank_mask:0xa
	v_sub_f32_dpp v101, v206, v206 row_shr:4 row_mask:0xf bank_mask:0xa
	v_sub_f32_dpp v18, v207, v207 row_shr:4 row_mask:0xf bank_mask:0xa
	v_max_f32_e64 v103, |v19|, |v102|
	v_max_f32_e64 v104, |v101|, |v18|
	v_max3_f32 v98, v98, v103, v104
	v_lshlrev_b32_e32 v103, 16, v16
	v_and_b32_e32 v16, 0xffff0000, v16
	v_lshlrev_b32_e32 v104, 16, v17
	v_and_b32_e32 v17, 0xffff0000, v17
	v_add_f32_e32 v105, v103, v16
	v_sub_f32_e32 v16, v103, v16
	v_add_f32_e32 v103, v104, v17
	v_sub_f32_e32 v17, v104, v17
	v_add_f32_e32 v104, v105, v103
	v_sub_f32_e32 v103, v105, v103
	v_add_f32_e32 v106, v16, v17
	v_sub_f32_e32 v16, v16, v17
	v_xor_b32_e32 v204, v82, v104
	v_xor_b32_e32 v205, v82, v103
	v_xor_b32_e32 v206, v82, v106
	v_xor_b32_e32 v207, v82, v16
	v_cvt_pk_bf16_f32 v19, v19, v102
	v_add_f32_dpp v17, v104, v204 quad_perm:[1,0,3,2] row_mask:0xf bank_mask:0xf bound_ctrl:1
	v_add_f32_dpp v103, v103, v205 quad_perm:[1,0,3,2] row_mask:0xf bank_mask:0xf bound_ctrl:1
	v_add_f32_dpp v104, v106, v206 quad_perm:[1,0,3,2] row_mask:0xf bank_mask:0xf bound_ctrl:1
	v_add_f32_dpp v16, v16, v207 quad_perm:[1,0,3,2] row_mask:0xf bank_mask:0xf bound_ctrl:1
	v_xor_b32_e32 v200, v83, v17
	v_xor_b32_e32 v201, v83, v104
	v_xor_b32_e32 v202, v83, v103
	v_xor_b32_e32 v203, v83, v16
	v_add_f32_dpp v204, v17, v200 quad_perm:[2,3,0,1] row_mask:0xf bank_mask:0xf bound_ctrl:1
	v_add_f32_dpp v205, v104, v201 quad_perm:[2,3,0,1] row_mask:0xf bank_mask:0xf bound_ctrl:1
	v_add_f32_dpp v206, v103, v202 quad_perm:[2,3,0,1] row_mask:0xf bank_mask:0xf bound_ctrl:1
	v_add_f32_dpp v207, v16, v203 quad_perm:[2,3,0,1] row_mask:0xf bank_mask:0xf bound_ctrl:1
	v_add_f32_dpp v17, v204, v204 row_shl:4 row_mask:0xf bank_mask:0x5
	v_add_f32_dpp v104, v205, v205 row_shl:4 row_mask:0xf bank_mask:0x5
	v_add_f32_dpp v103, v206, v206 row_shl:4 row_mask:0xf bank_mask:0x5
	v_add_f32_dpp v16, v207, v207 row_shl:4 row_mask:0xf bank_mask:0x5
	v_sub_f32_dpp v17, v204, v204 row_shr:4 row_mask:0xf bank_mask:0xa
	v_sub_f32_dpp v104, v205, v205 row_shr:4 row_mask:0xf bank_mask:0xa
	v_sub_f32_dpp v103, v206, v206 row_shr:4 row_mask:0xf bank_mask:0xa
	v_sub_f32_dpp v16, v207, v207 row_shr:4 row_mask:0xf bank_mask:0xa
	v_max_f32_e64 v105, |v17|, |v104|
	v_max_f32_e64 v106, |v103|, |v16|
	v_max3_f32 v98, v98, v105, v106
	v_lshlrev_b32_e32 v105, 16, v14
	v_and_b32_e32 v14, 0xffff0000, v14
	v_lshlrev_b32_e32 v106, 16, v15
	v_and_b32_e32 v15, 0xffff0000, v15
	v_add_f32_e32 v107, v105, v14
	v_sub_f32_e32 v14, v105, v14
	v_add_f32_e32 v105, v106, v15
	v_sub_f32_e32 v15, v106, v15
	v_add_f32_e32 v106, v107, v105
	v_sub_f32_e32 v105, v107, v105
	v_add_f32_e32 v108, v14, v15
	v_sub_f32_e32 v14, v14, v15
	v_xor_b32_e32 v204, v82, v106
	v_xor_b32_e32 v205, v82, v105
	v_xor_b32_e32 v206, v82, v108
	v_xor_b32_e32 v207, v82, v14
	v_add_f32_dpp v15, v106, v204 quad_perm:[1,0,3,2] row_mask:0xf bank_mask:0xf bound_ctrl:1
	v_add_f32_dpp v105, v105, v205 quad_perm:[1,0,3,2] row_mask:0xf bank_mask:0xf bound_ctrl:1
	v_add_f32_dpp v106, v108, v206 quad_perm:[1,0,3,2] row_mask:0xf bank_mask:0xf bound_ctrl:1
	v_add_f32_dpp v14, v14, v207 quad_perm:[1,0,3,2] row_mask:0xf bank_mask:0xf bound_ctrl:1
	v_xor_b32_e32 v200, v83, v15
	v_xor_b32_e32 v201, v83, v106
	v_xor_b32_e32 v202, v83, v105
	v_xor_b32_e32 v203, v83, v14
	v_add_f32_dpp v204, v15, v200 quad_perm:[2,3,0,1] row_mask:0xf bank_mask:0xf bound_ctrl:1
	v_add_f32_dpp v205, v106, v201 quad_perm:[2,3,0,1] row_mask:0xf bank_mask:0xf bound_ctrl:1
	v_add_f32_dpp v206, v105, v202 quad_perm:[2,3,0,1] row_mask:0xf bank_mask:0xf bound_ctrl:1
	v_add_f32_dpp v207, v14, v203 quad_perm:[2,3,0,1] row_mask:0xf bank_mask:0xf bound_ctrl:1
	v_add_f32_dpp v15, v204, v204 row_shl:4 row_mask:0xf bank_mask:0x5
	v_add_f32_dpp v106, v205, v205 row_shl:4 row_mask:0xf bank_mask:0x5
	v_add_f32_dpp v105, v206, v206 row_shl:4 row_mask:0xf bank_mask:0x5
	v_add_f32_dpp v14, v207, v207 row_shl:4 row_mask:0xf bank_mask:0x5
	v_sub_f32_dpp v15, v204, v204 row_shr:4 row_mask:0xf bank_mask:0xa
	v_sub_f32_dpp v106, v205, v205 row_shr:4 row_mask:0xf bank_mask:0xa
	v_sub_f32_dpp v105, v206, v206 row_shr:4 row_mask:0xf bank_mask:0xa
	v_sub_f32_dpp v14, v207, v207 row_shr:4 row_mask:0xf bank_mask:0xa
	v_max_f32_e64 v107, |v15|, |v106|
	v_max_f32_e64 v108, |v105|, |v14|
	v_max3_f32 v98, v98, v107, v108
	v_lshlrev_b32_e32 v107, 16, v12
	v_and_b32_e32 v12, 0xffff0000, v12
	v_lshlrev_b32_e32 v108, 16, v13
	v_and_b32_e32 v13, 0xffff0000, v13
	v_add_f32_e32 v109, v107, v12
	v_sub_f32_e32 v12, v107, v12
	v_add_f32_e32 v107, v108, v13
	v_sub_f32_e32 v13, v108, v13
	v_add_f32_e32 v108, v109, v107
	v_sub_f32_e32 v107, v109, v107
	v_add_f32_e32 v110, v12, v13
	v_sub_f32_e32 v12, v12, v13
	v_xor_b32_e32 v204, v82, v108
	v_xor_b32_e32 v205, v82, v107
	v_xor_b32_e32 v206, v82, v110
	v_xor_b32_e32 v207, v82, v12
	v_add_f32_dpp v13, v108, v204 quad_perm:[1,0,3,2] row_mask:0xf bank_mask:0xf bound_ctrl:1
	v_add_f32_dpp v107, v107, v205 quad_perm:[1,0,3,2] row_mask:0xf bank_mask:0xf bound_ctrl:1
	v_add_f32_dpp v108, v110, v206 quad_perm:[1,0,3,2] row_mask:0xf bank_mask:0xf bound_ctrl:1
	v_add_f32_dpp v12, v12, v207 quad_perm:[1,0,3,2] row_mask:0xf bank_mask:0xf bound_ctrl:1
	v_xor_b32_e32 v200, v83, v13
	v_xor_b32_e32 v201, v83, v108
	v_xor_b32_e32 v202, v83, v107
	v_xor_b32_e32 v203, v83, v12
	v_add_f32_dpp v204, v13, v200 quad_perm:[2,3,0,1] row_mask:0xf bank_mask:0xf bound_ctrl:1
	v_add_f32_dpp v205, v108, v201 quad_perm:[2,3,0,1] row_mask:0xf bank_mask:0xf bound_ctrl:1
	v_add_f32_dpp v206, v107, v202 quad_perm:[2,3,0,1] row_mask:0xf bank_mask:0xf bound_ctrl:1
	v_add_f32_dpp v207, v12, v203 quad_perm:[2,3,0,1] row_mask:0xf bank_mask:0xf bound_ctrl:1
	v_add_f32_dpp v13, v204, v204 row_shl:4 row_mask:0xf bank_mask:0x5
	v_add_f32_dpp v108, v205, v205 row_shl:4 row_mask:0xf bank_mask:0x5
	v_add_f32_dpp v107, v206, v206 row_shl:4 row_mask:0xf bank_mask:0x5
	v_add_f32_dpp v12, v207, v207 row_shl:4 row_mask:0xf bank_mask:0x5
	v_sub_f32_dpp v13, v204, v204 row_shr:4 row_mask:0xf bank_mask:0xa
	v_sub_f32_dpp v108, v205, v205 row_shr:4 row_mask:0xf bank_mask:0xa
	v_sub_f32_dpp v107, v206, v206 row_shr:4 row_mask:0xf bank_mask:0xa
	v_sub_f32_dpp v12, v207, v207 row_shr:4 row_mask:0xf bank_mask:0xa
	v_max_f32_e64 v109, |v13|, |v108|
	v_max_f32_e64 v110, |v107|, |v12|
	v_max3_f32 v98, v98, v109, v110
	v_lshlrev_b32_e32 v109, 16, v10
	v_and_b32_e32 v10, 0xffff0000, v10
	v_lshlrev_b32_e32 v110, 16, v11
	v_and_b32_e32 v11, 0xffff0000, v11
	v_add_f32_e32 v111, v109, v10
	v_sub_f32_e32 v10, v109, v10
	v_add_f32_e32 v109, v110, v11
	v_sub_f32_e32 v11, v110, v11
	v_add_f32_e32 v110, v111, v109
	v_sub_f32_e32 v109, v111, v109
	v_add_f32_e32 v112, v10, v11
	v_sub_f32_e32 v10, v10, v11
	v_xor_b32_e32 v204, v82, v110
	v_xor_b32_e32 v205, v82, v109
	v_xor_b32_e32 v206, v82, v112
	v_xor_b32_e32 v207, v82, v10
	v_add_f32_dpp v11, v110, v204 quad_perm:[1,0,3,2] row_mask:0xf bank_mask:0xf bound_ctrl:1
	v_add_f32_dpp v109, v109, v205 quad_perm:[1,0,3,2] row_mask:0xf bank_mask:0xf bound_ctrl:1
	v_add_f32_dpp v110, v112, v206 quad_perm:[1,0,3,2] row_mask:0xf bank_mask:0xf bound_ctrl:1
	v_add_f32_dpp v10, v10, v207 quad_perm:[1,0,3,2] row_mask:0xf bank_mask:0xf bound_ctrl:1
	v_xor_b32_e32 v200, v83, v11
	v_xor_b32_e32 v201, v83, v110
	v_xor_b32_e32 v202, v83, v109
	v_xor_b32_e32 v203, v83, v10
	v_add_f32_dpp v204, v11, v200 quad_perm:[2,3,0,1] row_mask:0xf bank_mask:0xf bound_ctrl:1
	v_add_f32_dpp v205, v110, v201 quad_perm:[2,3,0,1] row_mask:0xf bank_mask:0xf bound_ctrl:1
	v_add_f32_dpp v206, v109, v202 quad_perm:[2,3,0,1] row_mask:0xf bank_mask:0xf bound_ctrl:1
	v_add_f32_dpp v207, v10, v203 quad_perm:[2,3,0,1] row_mask:0xf bank_mask:0xf bound_ctrl:1
	v_add_f32_dpp v11, v204, v204 row_shl:4 row_mask:0xf bank_mask:0x5
	v_add_f32_dpp v110, v205, v205 row_shl:4 row_mask:0xf bank_mask:0x5
	v_add_f32_dpp v109, v206, v206 row_shl:4 row_mask:0xf bank_mask:0x5
	v_add_f32_dpp v10, v207, v207 row_shl:4 row_mask:0xf bank_mask:0x5
	v_sub_f32_dpp v11, v204, v204 row_shr:4 row_mask:0xf bank_mask:0xa
	v_sub_f32_dpp v110, v205, v205 row_shr:4 row_mask:0xf bank_mask:0xa
	v_sub_f32_dpp v109, v206, v206 row_shr:4 row_mask:0xf bank_mask:0xa
	v_sub_f32_dpp v10, v207, v207 row_shr:4 row_mask:0xf bank_mask:0xa
	v_max_f32_e64 v111, |v11|, |v110|
	v_max_f32_e64 v112, |v109|, |v10|
	v_max3_f32 v98, v98, v111, v112
	v_lshlrev_b32_e32 v111, 16, v8
	v_and_b32_e32 v8, 0xffff0000, v8
	v_lshlrev_b32_e32 v112, 16, v9
	v_and_b32_e32 v9, 0xffff0000, v9
	v_add_f32_e32 v113, v111, v8
	v_sub_f32_e32 v8, v111, v8
	v_add_f32_e32 v111, v112, v9
	v_sub_f32_e32 v9, v112, v9
	v_add_f32_e32 v112, v113, v111
	v_sub_f32_e32 v111, v113, v111
	v_add_f32_e32 v114, v8, v9
	v_sub_f32_e32 v8, v8, v9
	v_xor_b32_e32 v204, v82, v112
	v_xor_b32_e32 v205, v82, v111
	v_xor_b32_e32 v206, v82, v114
	v_xor_b32_e32 v207, v82, v8
	v_add_f32_dpp v9, v112, v204 quad_perm:[1,0,3,2] row_mask:0xf bank_mask:0xf bound_ctrl:1
	v_add_f32_dpp v111, v111, v205 quad_perm:[1,0,3,2] row_mask:0xf bank_mask:0xf bound_ctrl:1
	v_add_f32_dpp v112, v114, v206 quad_perm:[1,0,3,2] row_mask:0xf bank_mask:0xf bound_ctrl:1
	v_add_f32_dpp v8, v8, v207 quad_perm:[1,0,3,2] row_mask:0xf bank_mask:0xf bound_ctrl:1
	v_xor_b32_e32 v200, v83, v9
	v_xor_b32_e32 v201, v83, v112
	v_xor_b32_e32 v202, v83, v111
	v_xor_b32_e32 v203, v83, v8
	v_add_f32_dpp v204, v9, v200 quad_perm:[2,3,0,1] row_mask:0xf bank_mask:0xf bound_ctrl:1
	v_add_f32_dpp v205, v112, v201 quad_perm:[2,3,0,1] row_mask:0xf bank_mask:0xf bound_ctrl:1
	v_add_f32_dpp v206, v111, v202 quad_perm:[2,3,0,1] row_mask:0xf bank_mask:0xf bound_ctrl:1
	v_add_f32_dpp v207, v8, v203 quad_perm:[2,3,0,1] row_mask:0xf bank_mask:0xf bound_ctrl:1
	v_add_f32_dpp v9, v204, v204 row_shl:4 row_mask:0xf bank_mask:0x5
	v_add_f32_dpp v112, v205, v205 row_shl:4 row_mask:0xf bank_mask:0x5
	v_add_f32_dpp v111, v206, v206 row_shl:4 row_mask:0xf bank_mask:0x5
	v_add_f32_dpp v8, v207, v207 row_shl:4 row_mask:0xf bank_mask:0x5
	v_sub_f32_dpp v9, v204, v204 row_shr:4 row_mask:0xf bank_mask:0xa
	v_sub_f32_dpp v112, v205, v205 row_shr:4 row_mask:0xf bank_mask:0xa
	v_sub_f32_dpp v111, v206, v206 row_shr:4 row_mask:0xf bank_mask:0xa
	v_sub_f32_dpp v8, v207, v207 row_shr:4 row_mask:0xf bank_mask:0xa
	v_max_f32_e64 v113, |v9|, |v112|
	v_max_f32_e64 v114, |v111|, |v8|
	v_max3_f32 v98, v98, v113, v114
	v_lshlrev_b32_e32 v113, 16, v6
	v_and_b32_e32 v6, 0xffff0000, v6
	v_lshlrev_b32_e32 v114, 16, v7
	v_and_b32_e32 v7, 0xffff0000, v7
	v_add_f32_e32 v115, v113, v6
	v_sub_f32_e32 v6, v113, v6
	v_add_f32_e32 v113, v114, v7
	v_sub_f32_e32 v7, v114, v7
	v_add_f32_e32 v114, v115, v113
	v_sub_f32_e32 v113, v115, v113
	v_add_f32_e32 v116, v6, v7
	v_sub_f32_e32 v6, v6, v7
	v_xor_b32_e32 v204, v82, v114
	v_xor_b32_e32 v205, v82, v113
	v_xor_b32_e32 v206, v82, v116
	v_xor_b32_e32 v207, v82, v6
	v_add_f32_dpp v7, v114, v204 quad_perm:[1,0,3,2] row_mask:0xf bank_mask:0xf bound_ctrl:1
	v_add_f32_dpp v113, v113, v205 quad_perm:[1,0,3,2] row_mask:0xf bank_mask:0xf bound_ctrl:1
	v_add_f32_dpp v114, v116, v206 quad_perm:[1,0,3,2] row_mask:0xf bank_mask:0xf bound_ctrl:1
	v_add_f32_dpp v6, v6, v207 quad_perm:[1,0,3,2] row_mask:0xf bank_mask:0xf bound_ctrl:1
	v_xor_b32_e32 v200, v83, v7
	v_xor_b32_e32 v201, v83, v114
	v_xor_b32_e32 v202, v83, v113
	v_xor_b32_e32 v203, v83, v6
	v_add_f32_dpp v204, v7, v200 quad_perm:[2,3,0,1] row_mask:0xf bank_mask:0xf bound_ctrl:1
	v_add_f32_dpp v205, v114, v201 quad_perm:[2,3,0,1] row_mask:0xf bank_mask:0xf bound_ctrl:1
	v_add_f32_dpp v206, v113, v202 quad_perm:[2,3,0,1] row_mask:0xf bank_mask:0xf bound_ctrl:1
	v_add_f32_dpp v207, v6, v203 quad_perm:[2,3,0,1] row_mask:0xf bank_mask:0xf bound_ctrl:1
	v_add_f32_dpp v7, v204, v204 row_shl:4 row_mask:0xf bank_mask:0x5
	v_add_f32_dpp v114, v205, v205 row_shl:4 row_mask:0xf bank_mask:0x5
	v_add_f32_dpp v113, v206, v206 row_shl:4 row_mask:0xf bank_mask:0x5
	v_add_f32_dpp v6, v207, v207 row_shl:4 row_mask:0xf bank_mask:0x5
	v_sub_f32_dpp v7, v204, v204 row_shr:4 row_mask:0xf bank_mask:0xa
	v_sub_f32_dpp v114, v205, v205 row_shr:4 row_mask:0xf bank_mask:0xa
	v_sub_f32_dpp v113, v206, v206 row_shr:4 row_mask:0xf bank_mask:0xa
	v_sub_f32_dpp v6, v207, v207 row_shr:4 row_mask:0xf bank_mask:0xa
	v_max_f32_e64 v115, |v7|, |v114|
	v_max_f32_e64 v116, |v113|, |v6|
	v_max3_f32 v98, v98, v115, v116
	s_waitcnt vmcnt(0)
	v_lshlrev_b32_e32 v115, 16, v4
	v_and_b32_e32 v4, 0xffff0000, v4
	v_lshlrev_b32_e32 v116, 16, v5
	v_and_b32_e32 v5, 0xffff0000, v5
	v_add_f32_e32 v117, v115, v4
	v_sub_f32_e32 v4, v115, v4
	v_add_f32_e32 v115, v116, v5
	v_sub_f32_e32 v5, v116, v5
	v_add_f32_e32 v116, v117, v115
	v_sub_f32_e32 v115, v117, v115
	v_add_f32_e32 v118, v4, v5
	v_sub_f32_e32 v4, v4, v5
	v_xor_b32_e32 v204, v82, v116
	v_xor_b32_e32 v205, v82, v115
	v_xor_b32_e32 v206, v82, v118
	v_xor_b32_e32 v207, v82, v4
	v_add_f32_dpp v5, v116, v204 quad_perm:[1,0,3,2] row_mask:0xf bank_mask:0xf bound_ctrl:1
	v_add_f32_dpp v115, v115, v205 quad_perm:[1,0,3,2] row_mask:0xf bank_mask:0xf bound_ctrl:1
	v_add_f32_dpp v116, v118, v206 quad_perm:[1,0,3,2] row_mask:0xf bank_mask:0xf bound_ctrl:1
	v_add_f32_dpp v4, v4, v207 quad_perm:[1,0,3,2] row_mask:0xf bank_mask:0xf bound_ctrl:1
	v_xor_b32_e32 v200, v83, v5
	v_xor_b32_e32 v201, v83, v116
	v_xor_b32_e32 v202, v83, v115
	v_xor_b32_e32 v203, v83, v4
	v_add_f32_dpp v204, v5, v200 quad_perm:[2,3,0,1] row_mask:0xf bank_mask:0xf bound_ctrl:1
	v_add_f32_dpp v205, v116, v201 quad_perm:[2,3,0,1] row_mask:0xf bank_mask:0xf bound_ctrl:1
	v_add_f32_dpp v206, v115, v202 quad_perm:[2,3,0,1] row_mask:0xf bank_mask:0xf bound_ctrl:1
	v_add_f32_dpp v207, v4, v203 quad_perm:[2,3,0,1] row_mask:0xf bank_mask:0xf bound_ctrl:1
	v_add_f32_dpp v5, v204, v204 row_shl:4 row_mask:0xf bank_mask:0x5
	v_add_f32_dpp v116, v205, v205 row_shl:4 row_mask:0xf bank_mask:0x5
	v_add_f32_dpp v115, v206, v206 row_shl:4 row_mask:0xf bank_mask:0x5
	v_add_f32_dpp v4, v207, v207 row_shl:4 row_mask:0xf bank_mask:0x5
	v_sub_f32_dpp v5, v204, v204 row_shr:4 row_mask:0xf bank_mask:0xa
	v_sub_f32_dpp v116, v205, v205 row_shr:4 row_mask:0xf bank_mask:0xa
	v_sub_f32_dpp v115, v206, v206 row_shr:4 row_mask:0xf bank_mask:0xa
	v_sub_f32_dpp v4, v207, v207 row_shr:4 row_mask:0xf bank_mask:0xa
	v_max_f32_e64 v117, |v5|, |v116|
	v_max_f32_e64 v118, |v115|, |v4|
	v_max3_f32 v98, v98, v117, v118
	ds_swizzle_b32 v117, v98 offset:swizzle(SWAP,1)
	s_waitcnt lgkmcnt(0)
	v_max_f32_e32 v94, v117, v117
	v_max_f32_e32 v94, v98, v94
	ds_swizzle_b32 v95, v94 offset:swizzle(SWAP,2)
	v_cvt_pk_bf16_f32 v98, v101, v18
	s_waitcnt lgkmcnt(0)
	v_max_f32_e32 v18, v95, v95
	v_max_f32_e32 v18, v94, v18
	ds_swizzle_b32 v20, v18 offset:swizzle(SWAP,4)
	v_cvt_pk_bf16_f32 v94, v17, v104
	v_cvt_pk_bf16_f32 v95, v103, v16
	v_cvt_pk_bf16_f32 v99, v15, v106
	v_cvt_pk_bf16_f32 v100, v105, v14
	s_waitcnt lgkmcnt(0)
	v_max_f32_e32 v14, v20, v20
	v_max_f32_e32 v14, v18, v14
	ds_swizzle_b32 v16, v14 offset:swizzle(SWAP,8)
	v_cvt_pk_bf16_f32 v18, v13, v108
	v_cvt_pk_bf16_f32 v101, v107, v12
	v_cvt_pk_bf16_f32 v15, v11, v110
	v_cvt_pk_bf16_f32 v17, v109, v10
	s_waitcnt lgkmcnt(0)
	v_max_f32_e32 v10, v16, v16
	v_max_f32_e32 v10, v14, v10
	ds_swizzle_b32 v12, v10 offset:swizzle(SWAP,16)
	v_cvt_pk_bf16_f32 v13, v9, v112
	v_cvt_pk_bf16_f32 v14, v111, v8
	v_cvt_pk_bf16_f32 v9, v7, v114
	v_cvt_pk_bf16_f32 v11, v113, v6
	s_waitcnt lgkmcnt(0)
	v_max_f32_e32 v6, v12, v12
	v_max_f32_e32 v6, v10, v6
	v_mov_b32_e32 v7, v6
	s_nop 1
	v_permlane32_swap_b32_e32 v6, v7
	v_max_f32_e32 v7, v7, v7
	v_max_f32_e32 v6, v6, v6
	v_max_f32_e32 v6, v6, v7
	v_mul_f32_e32 v8, 0x3f808000, v6
	v_div_scale_f32 v6, s[18:19], v8, v8, s27
	v_rcp_f32_e32 v7, v6
	v_cvt_pk_bf16_f32 v10, v5, v116
	v_cvt_pk_bf16_f32 v12, v115, v4
	v_lshl_add_u64 v[4:5], s[8:9], 0, v[0:1]
	v_fma_f32 v16, -v6, v7, 1.0
	v_fmac_f32_e32 v7, v16, v7
	v_div_scale_f32 v16, vcc, s27, v8, s27
	v_mul_f32_e32 v20, v16, v7
	v_fma_f32 v21, -v6, v20, v16
	v_fmac_f32_e32 v20, v21, v7
	v_fma_f32 v6, -v6, v20, v16
	v_div_fmas_f32 v6, v6, v7, v20
	v_div_fixup_f32 v6, v6, v8, s27
	v_cmp_lt_f32_e32 vcc, 0, v8
	v_lshlrev_b32_e32 v7, 16, v87
	v_lshlrev_b32_e32 v20, 16, v86
	v_cndmask_b32_e32 v16, 0, v6, vcc
	v_and_b32_e32 v6, 0xffff0000, v87
	v_fmaak_f32 v6, v6, v16, 0x4b400000
	v_fmaak_f32 v7, v7, v16, 0x4b400000
	v_perm_b32 v6, v6, v7, s28
	v_and_b32_e32 v7, 0xffff0000, v86
	v_fmaak_f32 v7, v7, v16, 0x4b400000
	v_fmaak_f32 v20, v20, v16, 0x4b400000
	v_perm_b32 v7, v7, v20, s28
	v_add_co_u32_e32 v20, vcc, s30, v4
	v_perm_b32 v86, v6, v7, s29
	s_nop 0
	v_addc_co_u32_e32 v21, vcc, 0, v5, vcc
	v_add_co_u32_e32 v6, vcc, s31, v4
	v_lshlrev_b32_e32 v87, 16, v89
	s_nop 0
	v_addc_co_u32_e32 v7, vcc, 0, v5, vcc
	global_store_dword v[6:7], v86, off offset:-4096 nt
	v_and_b32_e32 v86, 0xffff0000, v89
	v_fmaak_f32 v86, v86, v16, 0x4b400000
	v_fmaak_f32 v87, v87, v16, 0x4b400000
	v_perm_b32 v86, v86, v87, s28
	v_and_b32_e32 v87, 0xffff0000, v88
	v_lshlrev_b32_e32 v88, 16, v88
	v_fmaak_f32 v87, v87, v16, 0x4b400000
	v_fmaak_f32 v88, v88, v16, 0x4b400000
	v_perm_b32 v87, v87, v88, s28
	v_perm_b32 v86, v86, v87, s29
	global_store_dword v[20:21], v86, off offset:256 nt
	v_and_b32_e32 v86, 0xffff0000, v91
	v_lshlrev_b32_e32 v87, 16, v91
	v_fmaak_f32 v86, v86, v16, 0x4b400000
	v_fmaak_f32 v87, v87, v16, 0x4b400000
	v_perm_b32 v86, v86, v87, s28
	v_and_b32_e32 v87, 0xffff0000, v90
	v_lshlrev_b32_e32 v88, 16, v90
	v_fmaak_f32 v87, v87, v16, 0x4b400000
	v_fmaak_f32 v88, v88, v16, 0x4b400000
	v_perm_b32 v87, v87, v88, s28
	v_perm_b32 v86, v86, v87, s29
	global_store_dword v[20:21], v86, off offset:512 nt
	v_and_b32_e32 v86, 0xffff0000, v93
	v_lshlrev_b32_e32 v87, 16, v93
	v_fmaak_f32 v86, v86, v16, 0x4b400000
	v_fmaak_f32 v87, v87, v16, 0x4b400000
	v_perm_b32 v86, v86, v87, s28
	v_and_b32_e32 v87, 0xffff0000, v92
	v_lshlrev_b32_e32 v88, 16, v92
	v_fmaak_f32 v87, v87, v16, 0x4b400000
	v_fmaak_f32 v88, v88, v16, 0x4b400000
	v_perm_b32 v87, v87, v88, s28
	v_perm_b32 v86, v86, v87, s29
	global_store_dword v[20:21], v86, off offset:768 nt
	v_and_b32_e32 v86, 0xffff0000, v81
	v_lshlrev_b32_e32 v81, 16, v81
	v_fmaak_f32 v86, v86, v16, 0x4b400000
	v_fmaak_f32 v81, v81, v16, 0x4b400000
	v_perm_b32 v81, v86, v81, s28
	v_and_b32_e32 v86, 0xffff0000, v80
	v_lshlrev_b32_e32 v80, 16, v80
	v_fmaak_f32 v86, v86, v16, 0x4b400000
	v_fmaak_f32 v80, v80, v16, 0x4b400000
	v_perm_b32 v80, v86, v80, s28
	v_perm_b32 v80, v81, v80, s29
	global_store_dword v[20:21], v80, off offset:1024 nt
	v_and_b32_e32 v80, 0xffff0000, v79
	v_lshlrev_b32_e32 v79, 16, v79
	v_fmaak_f32 v80, v80, v16, 0x4b400000
	v_fmaak_f32 v79, v79, v16, 0x4b400000
	v_perm_b32 v79, v80, v79, s28
	v_and_b32_e32 v80, 0xffff0000, v78
	v_lshlrev_b32_e32 v78, 16, v78
	v_fmaak_f32 v80, v80, v16, 0x4b400000
	v_fmaak_f32 v78, v78, v16, 0x4b400000
	v_perm_b32 v78, v80, v78, s28
	v_perm_b32 v78, v79, v78, s29
	global_store_dword v[20:21], v78, off offset:1280 nt
	v_and_b32_e32 v78, 0xffff0000, v77
	v_lshlrev_b32_e32 v77, 16, v77
	v_fmaak_f32 v78, v78, v16, 0x4b400000
	v_fmaak_f32 v77, v77, v16, 0x4b400000
	v_perm_b32 v77, v78, v77, s28
	v_and_b32_e32 v78, 0xffff0000, v76
	v_lshlrev_b32_e32 v76, 16, v76
	v_fmaak_f32 v78, v78, v16, 0x4b400000
	v_fmaak_f32 v76, v76, v16, 0x4b400000
	v_perm_b32 v76, v78, v76, s28
	v_perm_b32 v76, v77, v76, s29
	global_store_dword v[20:21], v76, off offset:1536 nt
	v_and_b32_e32 v76, 0xffff0000, v75
	v_lshlrev_b32_e32 v75, 16, v75
	v_fmaak_f32 v76, v76, v16, 0x4b400000
	v_fmaak_f32 v75, v75, v16, 0x4b400000
	v_perm_b32 v75, v76, v75, s28
	v_and_b32_e32 v76, 0xffff0000, v74
	v_lshlrev_b32_e32 v74, 16, v74
	v_fmaak_f32 v76, v76, v16, 0x4b400000
	v_fmaak_f32 v74, v74, v16, 0x4b400000
	v_perm_b32 v74, v76, v74, s28
	v_perm_b32 v74, v75, v74, s29
	global_store_dword v[20:21], v74, off offset:1792 nt
	v_and_b32_e32 v74, 0xffff0000, v73
	v_lshlrev_b32_e32 v73, 16, v73
	v_fmaak_f32 v74, v74, v16, 0x4b400000
	v_fmaak_f32 v73, v73, v16, 0x4b400000
	v_perm_b32 v73, v74, v73, s28
	v_and_b32_e32 v74, 0xffff0000, v72
	v_lshlrev_b32_e32 v72, 16, v72
	v_fmaak_f32 v74, v74, v16, 0x4b400000
	v_fmaak_f32 v72, v72, v16, 0x4b400000
	v_perm_b32 v72, v74, v72, s28
	v_perm_b32 v72, v73, v72, s29
	global_store_dword v[20:21], v72, off offset:2048 nt
	v_and_b32_e32 v72, 0xffff0000, v71
	v_lshlrev_b32_e32 v71, 16, v71
	v_fmaak_f32 v72, v72, v16, 0x4b400000
	v_fmaak_f32 v71, v71, v16, 0x4b400000
	v_perm_b32 v71, v72, v71, s28
	v_and_b32_e32 v72, 0xffff0000, v70
	v_lshlrev_b32_e32 v70, 16, v70
	v_fmaak_f32 v72, v72, v16, 0x4b400000
	v_fmaak_f32 v70, v70, v16, 0x4b400000
	v_perm_b32 v70, v72, v70, s28
	v_perm_b32 v70, v71, v70, s29
	global_store_dword v[20:21], v70, off offset:2304 nt
	v_and_b32_e32 v70, 0xffff0000, v69
	v_lshlrev_b32_e32 v69, 16, v69
	v_fmaak_f32 v70, v70, v16, 0x4b400000
	v_fmaak_f32 v69, v69, v16, 0x4b400000
	v_perm_b32 v69, v70, v69, s28
	v_and_b32_e32 v70, 0xffff0000, v68
	v_lshlrev_b32_e32 v68, 16, v68
	v_fmaak_f32 v70, v70, v16, 0x4b400000
	v_fmaak_f32 v68, v68, v16, 0x4b400000
	v_perm_b32 v68, v70, v68, s28
	v_perm_b32 v68, v69, v68, s29
	global_store_dword v[20:21], v68, off offset:2560 nt
	v_and_b32_e32 v68, 0xffff0000, v67
	v_lshlrev_b32_e32 v67, 16, v67
	v_fmaak_f32 v68, v68, v16, 0x4b400000
	v_fmaak_f32 v67, v67, v16, 0x4b400000
	v_perm_b32 v67, v68, v67, s28
	v_and_b32_e32 v68, 0xffff0000, v66
	v_lshlrev_b32_e32 v66, 16, v66
	v_fmaak_f32 v68, v68, v16, 0x4b400000
	v_fmaak_f32 v66, v66, v16, 0x4b400000
	v_perm_b32 v66, v68, v66, s28
	v_perm_b32 v66, v67, v66, s29
	global_store_dword v[20:21], v66, off offset:2816 nt
	v_and_b32_e32 v66, 0xffff0000, v65
	v_lshlrev_b32_e32 v65, 16, v65
	v_fmaak_f32 v66, v66, v16, 0x4b400000
	v_fmaak_f32 v65, v65, v16, 0x4b400000
	v_perm_b32 v65, v66, v65, s28
	v_and_b32_e32 v66, 0xffff0000, v64
	v_lshlrev_b32_e32 v64, 16, v64
	v_fmaak_f32 v66, v66, v16, 0x4b400000
	v_fmaak_f32 v64, v64, v16, 0x4b400000
	v_perm_b32 v64, v66, v64, s28
	v_perm_b32 v64, v65, v64, s29
	global_store_dword v[20:21], v64, off offset:3072 nt
	v_and_b32_e32 v64, 0xffff0000, v63
	v_lshlrev_b32_e32 v63, 16, v63
	v_fmaak_f32 v64, v64, v16, 0x4b400000
	v_fmaak_f32 v63, v63, v16, 0x4b400000
	v_perm_b32 v63, v64, v63, s28
	v_and_b32_e32 v64, 0xffff0000, v62
	v_lshlrev_b32_e32 v62, 16, v62
	v_fmaak_f32 v64, v64, v16, 0x4b400000
	v_fmaak_f32 v62, v62, v16, 0x4b400000
	v_perm_b32 v62, v64, v62, s28
	v_perm_b32 v62, v63, v62, s29
	global_store_dword v[20:21], v62, off offset:3328 nt
	v_and_b32_e32 v62, 0xffff0000, v61
	v_lshlrev_b32_e32 v61, 16, v61
	v_fmaak_f32 v62, v62, v16, 0x4b400000
	v_fmaak_f32 v61, v61, v16, 0x4b400000
	v_perm_b32 v61, v62, v61, s28
	v_and_b32_e32 v62, 0xffff0000, v60
	v_lshlrev_b32_e32 v60, 16, v60
	v_fmaak_f32 v62, v62, v16, 0x4b400000
	v_fmaak_f32 v60, v60, v16, 0x4b400000
	v_perm_b32 v60, v62, v60, s28
	v_perm_b32 v60, v61, v60, s29
	global_store_dword v[20:21], v60, off offset:3584 nt
	v_and_b32_e32 v60, 0xffff0000, v59
	v_lshlrev_b32_e32 v59, 16, v59
	v_fmaak_f32 v60, v60, v16, 0x4b400000
	v_fmaak_f32 v59, v59, v16, 0x4b400000
	v_perm_b32 v59, v60, v59, s28
	v_and_b32_e32 v60, 0xffff0000, v58
	v_lshlrev_b32_e32 v58, 16, v58
	v_fmaak_f32 v60, v60, v16, 0x4b400000
	v_fmaak_f32 v58, v58, v16, 0x4b400000
	v_perm_b32 v58, v60, v58, s28
	v_perm_b32 v58, v59, v58, s29
	global_store_dword v[20:21], v58, off offset:3840 nt
	v_and_b32_e32 v20, 0xffff0000, v57
	v_lshlrev_b32_e32 v21, 16, v57
	v_fmaak_f32 v20, v20, v16, 0x4b400000
	v_fmaak_f32 v21, v21, v16, 0x4b400000
	v_perm_b32 v20, v20, v21, s28
	v_and_b32_e32 v21, 0xffff0000, v56
	v_lshlrev_b32_e32 v56, 16, v56
	v_fmaak_f32 v21, v21, v16, 0x4b400000
	v_fmaak_f32 v56, v56, v16, 0x4b400000
	v_perm_b32 v21, v21, v56, s28
	v_perm_b32 v20, v20, v21, s29
	global_store_dword v[6:7], v20, off nt
	v_and_b32_e32 v20, 0xffff0000, v55
	v_lshlrev_b32_e32 v21, 16, v55
	v_fmaak_f32 v20, v20, v16, 0x4b400000
	v_fmaak_f32 v21, v21, v16, 0x4b400000
	v_perm_b32 v20, v20, v21, s28
	v_and_b32_e32 v21, 0xffff0000, v54
	v_lshlrev_b32_e32 v54, 16, v54
	v_fmaak_f32 v21, v21, v16, 0x4b400000
	v_fmaak_f32 v54, v54, v16, 0x4b400000
	v_perm_b32 v21, v21, v54, s28
	v_perm_b32 v20, v20, v21, s29
	global_store_dword v[6:7], v20, off offset:256 nt
	v_and_b32_e32 v20, 0xffff0000, v53
	v_lshlrev_b32_e32 v21, 16, v53
	v_fmaak_f32 v20, v20, v16, 0x4b400000
	v_fmaak_f32 v21, v21, v16, 0x4b400000
	v_perm_b32 v20, v20, v21, s28
	v_and_b32_e32 v21, 0xffff0000, v52
	v_lshlrev_b32_e32 v52, 16, v52
	v_fmaak_f32 v21, v21, v16, 0x4b400000
	v_fmaak_f32 v52, v52, v16, 0x4b400000
	v_perm_b32 v21, v21, v52, s28
	v_perm_b32 v20, v20, v21, s29
	global_store_dword v[6:7], v20, off offset:512 nt
	v_and_b32_e32 v20, 0xffff0000, v51
	v_lshlrev_b32_e32 v21, 16, v51
	v_fmaak_f32 v20, v20, v16, 0x4b400000
	v_fmaak_f32 v21, v21, v16, 0x4b400000
	v_perm_b32 v20, v20, v21, s28
	v_and_b32_e32 v21, 0xffff0000, v50
	v_lshlrev_b32_e32 v50, 16, v50
	v_fmaak_f32 v21, v21, v16, 0x4b400000
	v_fmaak_f32 v50, v50, v16, 0x4b400000
	v_perm_b32 v21, v21, v50, s28
	v_perm_b32 v20, v20, v21, s29
	global_store_dword v[6:7], v20, off offset:768 nt
	v_and_b32_e32 v20, 0xffff0000, v49
	v_lshlrev_b32_e32 v21, 16, v49
	v_fmaak_f32 v20, v20, v16, 0x4b400000
	v_fmaak_f32 v21, v21, v16, 0x4b400000
	v_perm_b32 v20, v20, v21, s28
	v_and_b32_e32 v21, 0xffff0000, v48
	v_lshlrev_b32_e32 v48, 16, v48
	v_fmaak_f32 v21, v21, v16, 0x4b400000
	v_fmaak_f32 v48, v48, v16, 0x4b400000
	v_perm_b32 v21, v21, v48, s28
	v_perm_b32 v20, v20, v21, s29
	global_store_dword v[6:7], v20, off offset:1024 nt
	v_and_b32_e32 v20, 0xffff0000, v47
	v_lshlrev_b32_e32 v21, 16, v47
	v_fmaak_f32 v20, v20, v16, 0x4b400000
	v_fmaak_f32 v21, v21, v16, 0x4b400000
	v_perm_b32 v20, v20, v21, s28
	v_and_b32_e32 v21, 0xffff0000, v46
	v_lshlrev_b32_e32 v46, 16, v46
	v_fmaak_f32 v21, v21, v16, 0x4b400000
	v_fmaak_f32 v46, v46, v16, 0x4b400000
	v_perm_b32 v21, v21, v46, s28
	v_perm_b32 v20, v20, v21, s29
	global_store_dword v[6:7], v20, off offset:1280 nt
	v_and_b32_e32 v20, 0xffff0000, v45
	v_lshlrev_b32_e32 v21, 16, v45
	v_fmaak_f32 v20, v20, v16, 0x4b400000
	v_fmaak_f32 v21, v21, v16, 0x4b400000
	v_perm_b32 v20, v20, v21, s28
	v_and_b32_e32 v21, 0xffff0000, v44
	v_lshlrev_b32_e32 v44, 16, v44
	v_fmaak_f32 v21, v21, v16, 0x4b400000
	v_fmaak_f32 v44, v44, v16, 0x4b400000
	v_perm_b32 v21, v21, v44, s28
	v_perm_b32 v20, v20, v21, s29
	global_store_dword v[6:7], v20, off offset:1536 nt
	v_and_b32_e32 v20, 0xffff0000, v43
	v_lshlrev_b32_e32 v21, 16, v43
	v_fmaak_f32 v20, v20, v16, 0x4b400000
	v_fmaak_f32 v21, v21, v16, 0x4b400000
	v_perm_b32 v20, v20, v21, s28
	v_and_b32_e32 v21, 0xffff0000, v42
	v_lshlrev_b32_e32 v42, 16, v42
	v_fmaak_f32 v21, v21, v16, 0x4b400000
	v_fmaak_f32 v42, v42, v16, 0x4b400000
	v_perm_b32 v21, v21, v42, s28
	v_perm_b32 v20, v20, v21, s29
	global_store_dword v[6:7], v20, off offset:1792 nt
	v_and_b32_e32 v20, 0xffff0000, v41
	v_lshlrev_b32_e32 v21, 16, v41
	v_fmaak_f32 v20, v20, v16, 0x4b400000
	v_fmaak_f32 v21, v21, v16, 0x4b400000
	v_perm_b32 v20, v20, v21, s28
	v_and_b32_e32 v21, 0xffff0000, v40
	v_lshlrev_b32_e32 v40, 16, v40
	v_fmaak_f32 v21, v21, v16, 0x4b400000
	v_fmaak_f32 v40, v40, v16, 0x4b400000
	v_perm_b32 v21, v21, v40, s28
	v_perm_b32 v20, v20, v21, s29
	global_store_dword v[6:7], v20, off offset:2048 nt
	v_and_b32_e32 v20, 0xffff0000, v39
	v_lshlrev_b32_e32 v21, 16, v39
	v_fmaak_f32 v20, v20, v16, 0x4b400000
	v_fmaak_f32 v21, v21, v16, 0x4b400000
	v_perm_b32 v20, v20, v21, s28
	v_and_b32_e32 v21, 0xffff0000, v38
	v_lshlrev_b32_e32 v38, 16, v38
	v_fmaak_f32 v21, v21, v16, 0x4b400000
	v_fmaak_f32 v38, v38, v16, 0x4b400000
	v_perm_b32 v21, v21, v38, s28
	v_perm_b32 v20, v20, v21, s29
	global_store_dword v[6:7], v20, off offset:2304 nt
	v_and_b32_e32 v20, 0xffff0000, v37
	v_lshlrev_b32_e32 v21, 16, v37
	v_fmaak_f32 v20, v20, v16, 0x4b400000
	v_fmaak_f32 v21, v21, v16, 0x4b400000
	v_perm_b32 v20, v20, v21, s28
	v_and_b32_e32 v21, 0xffff0000, v36
	v_lshlrev_b32_e32 v36, 16, v36
	v_fmaak_f32 v21, v21, v16, 0x4b400000
	v_fmaak_f32 v36, v36, v16, 0x4b400000
	v_perm_b32 v21, v21, v36, s28
	v_perm_b32 v20, v20, v21, s29
	global_store_dword v[6:7], v20, off offset:2560 nt
	v_and_b32_e32 v20, 0xffff0000, v35
	v_lshlrev_b32_e32 v21, 16, v35
	v_fmaak_f32 v20, v20, v16, 0x4b400000
	v_fmaak_f32 v21, v21, v16, 0x4b400000
	v_perm_b32 v20, v20, v21, s28
	v_and_b32_e32 v21, 0xffff0000, v34
	v_lshlrev_b32_e32 v34, 16, v34
	v_fmaak_f32 v21, v21, v16, 0x4b400000
	v_fmaak_f32 v34, v34, v16, 0x4b400000
	v_perm_b32 v21, v21, v34, s28
	v_perm_b32 v20, v20, v21, s29
	global_store_dword v[6:7], v20, off offset:2816 nt
	v_and_b32_e32 v20, 0xffff0000, v33
	v_lshlrev_b32_e32 v21, 16, v33
	v_fmaak_f32 v20, v20, v16, 0x4b400000
	v_fmaak_f32 v21, v21, v16, 0x4b400000
	v_perm_b32 v20, v20, v21, s28
	v_and_b32_e32 v21, 0xffff0000, v32
	v_lshlrev_b32_e32 v32, 16, v32
	v_fmaak_f32 v21, v21, v16, 0x4b400000
	v_fmaak_f32 v32, v32, v16, 0x4b400000
	v_perm_b32 v21, v21, v32, s28
	v_perm_b32 v20, v20, v21, s29
	global_store_dword v[6:7], v20, off offset:3072 nt
	v_and_b32_e32 v20, 0xffff0000, v31
	v_lshlrev_b32_e32 v21, 16, v31
	v_fmaak_f32 v20, v20, v16, 0x4b400000
	v_fmaak_f32 v21, v21, v16, 0x4b400000
	v_perm_b32 v20, v20, v21, s28
	v_and_b32_e32 v21, 0xffff0000, v30
	v_lshlrev_b32_e32 v30, 16, v30
	v_fmaak_f32 v21, v21, v16, 0x4b400000
	v_fmaak_f32 v30, v30, v16, 0x4b400000
	v_perm_b32 v21, v21, v30, s28
	v_perm_b32 v20, v20, v21, s29
	global_store_dword v[6:7], v20, off offset:3328 nt
	v_and_b32_e32 v20, 0xffff0000, v29
	v_lshlrev_b32_e32 v21, 16, v29
	v_fmaak_f32 v20, v20, v16, 0x4b400000
	v_fmaak_f32 v21, v21, v16, 0x4b400000
	v_perm_b32 v20, v20, v21, s28
	v_and_b32_e32 v21, 0xffff0000, v28
	v_lshlrev_b32_e32 v28, 16, v28
	v_fmaak_f32 v21, v21, v16, 0x4b400000
	v_fmaak_f32 v28, v28, v16, 0x4b400000
	v_perm_b32 v21, v21, v28, s28
	v_perm_b32 v20, v20, v21, s29
	global_store_dword v[6:7], v20, off offset:3584 nt
	v_and_b32_e32 v20, 0xffff0000, v27
	v_lshlrev_b32_e32 v21, 16, v27
	v_fmaak_f32 v20, v20, v16, 0x4b400000
	v_fmaak_f32 v21, v21, v16, 0x4b400000
	v_perm_b32 v20, v20, v21, s28
	v_and_b32_e32 v21, 0xffff0000, v26
	v_lshlrev_b32_e32 v26, 16, v26
	v_fmaak_f32 v21, v21, v16, 0x4b400000
	v_fmaak_f32 v26, v26, v16, 0x4b400000
	v_perm_b32 v21, v21, v26, s28
	v_perm_b32 v20, v20, v21, s29
	global_store_dword v[6:7], v20, off offset:3840 nt
	v_and_b32_e32 v6, 0xffff0000, v25
	v_lshlrev_b32_e32 v7, 16, v25
	v_fmaak_f32 v6, v6, v16, 0x4b400000
	v_fmaak_f32 v7, v7, v16, 0x4b400000
	v_perm_b32 v6, v6, v7, s28
	v_and_b32_e32 v7, 0xffff0000, v24
	v_lshlrev_b32_e32 v20, 16, v24
	v_fmaak_f32 v7, v7, v16, 0x4b400000
	v_fmaak_f32 v20, v20, v16, 0x4b400000
	v_perm_b32 v7, v7, v20, s28
	v_add_co_u32_e32 v4, vcc, s34, v4
	v_perm_b32 v6, v6, v7, s29
	s_nop 0
	v_addc_co_u32_e32 v5, vcc, 0, v5, vcc
	global_store_dword v[4:5], v6, off nt
	v_and_b32_e32 v6, 0xffff0000, v23
	v_lshlrev_b32_e32 v7, 16, v23
	v_fmaak_f32 v6, v6, v16, 0x4b400000
	v_fmaak_f32 v7, v7, v16, 0x4b400000
	v_perm_b32 v6, v6, v7, s28
	v_and_b32_e32 v7, 0xffff0000, v22
	v_lshlrev_b32_e32 v20, 16, v22
	v_fmaak_f32 v7, v7, v16, 0x4b400000
	v_fmaak_f32 v20, v20, v16, 0x4b400000
	v_perm_b32 v7, v7, v20, s28
	v_perm_b32 v6, v6, v7, s29
	global_store_dword v[4:5], v6, off offset:256 nt
	v_and_b32_e32 v6, 0xffff0000, v97
	v_lshlrev_b32_e32 v7, 16, v97
	v_fmaak_f32 v6, v6, v16, 0x4b400000
	v_fmaak_f32 v7, v7, v16, 0x4b400000
	v_perm_b32 v6, v6, v7, s28
	v_and_b32_e32 v7, 0xffff0000, v96
	v_lshlrev_b32_e32 v20, 16, v96
	v_fmaak_f32 v7, v7, v16, 0x4b400000
	v_fmaak_f32 v20, v20, v16, 0x4b400000
	v_perm_b32 v7, v7, v20, s28
	v_perm_b32 v6, v6, v7, s29
	global_store_dword v[4:5], v6, off offset:512 nt
	v_and_b32_e32 v6, 0xffff0000, v98
	v_lshlrev_b32_e32 v7, 16, v98
	v_fmaak_f32 v6, v6, v16, 0x4b400000
	v_fmaak_f32 v7, v7, v16, 0x4b400000
	v_perm_b32 v6, v6, v7, s28
	v_and_b32_e32 v7, 0xffff0000, v19
	v_lshlrev_b32_e32 v19, 16, v19
	v_fmaak_f32 v7, v7, v16, 0x4b400000
	v_fmaak_f32 v19, v19, v16, 0x4b400000
	v_perm_b32 v7, v7, v19, s28
	v_perm_b32 v6, v6, v7, s29
	global_store_dword v[4:5], v6, off offset:768 nt
	v_and_b32_e32 v6, 0xffff0000, v95
	v_lshlrev_b32_e32 v7, 16, v95
	v_fmaak_f32 v6, v6, v16, 0x4b400000
	v_fmaak_f32 v7, v7, v16, 0x4b400000
	v_perm_b32 v6, v6, v7, s28
	v_and_b32_e32 v7, 0xffff0000, v94
	v_lshlrev_b32_e32 v19, 16, v94
	v_fmaak_f32 v7, v7, v16, 0x4b400000
	v_fmaak_f32 v19, v19, v16, 0x4b400000
	v_perm_b32 v7, v7, v19, s28
	v_perm_b32 v6, v6, v7, s29
	global_store_dword v[4:5], v6, off offset:1024 nt
	v_and_b32_e32 v6, 0xffff0000, v100
	v_lshlrev_b32_e32 v7, 16, v100
	v_fmaak_f32 v6, v6, v16, 0x4b400000
	v_fmaak_f32 v7, v7, v16, 0x4b400000
	v_perm_b32 v6, v6, v7, s28
	v_and_b32_e32 v7, 0xffff0000, v99
	v_lshlrev_b32_e32 v19, 16, v99
	v_fmaak_f32 v7, v7, v16, 0x4b400000
	v_fmaak_f32 v19, v19, v16, 0x4b400000
	v_perm_b32 v7, v7, v19, s28
	v_perm_b32 v6, v6, v7, s29
	global_store_dword v[4:5], v6, off offset:1280 nt
	v_and_b32_e32 v6, 0xffff0000, v101
	v_lshlrev_b32_e32 v7, 16, v101
	v_fmaak_f32 v6, v6, v16, 0x4b400000
	v_fmaak_f32 v7, v7, v16, 0x4b400000
	v_perm_b32 v6, v6, v7, s28
	v_and_b32_e32 v7, 0xffff0000, v18
	v_lshlrev_b32_e32 v18, 16, v18
	v_fmaak_f32 v7, v7, v16, 0x4b400000
	v_fmaak_f32 v18, v18, v16, 0x4b400000
	v_perm_b32 v7, v7, v18, s28
	v_perm_b32 v6, v6, v7, s29
	global_store_dword v[4:5], v6, off offset:1536 nt
	v_and_b32_e32 v6, 0xffff0000, v17
	v_lshlrev_b32_e32 v7, 16, v17
	v_fmaak_f32 v6, v6, v16, 0x4b400000
	v_fmaak_f32 v7, v7, v16, 0x4b400000
	v_perm_b32 v6, v6, v7, s28
	v_and_b32_e32 v7, 0xffff0000, v15
	v_lshlrev_b32_e32 v15, 16, v15
	v_fmaak_f32 v7, v7, v16, 0x4b400000
	v_fmaak_f32 v15, v15, v16, 0x4b400000
	v_perm_b32 v7, v7, v15, s28
	v_perm_b32 v6, v6, v7, s29
	global_store_dword v[4:5], v6, off offset:1792 nt
	v_and_b32_e32 v6, 0xffff0000, v14
	v_lshlrev_b32_e32 v7, 16, v14
	v_fmaak_f32 v6, v6, v16, 0x4b400000
	v_fmaak_f32 v7, v7, v16, 0x4b400000
	v_perm_b32 v6, v6, v7, s28
	v_and_b32_e32 v7, 0xffff0000, v13
	v_lshlrev_b32_e32 v13, 16, v13
	v_fmaak_f32 v7, v7, v16, 0x4b400000
	v_fmaak_f32 v13, v13, v16, 0x4b400000
	v_perm_b32 v7, v7, v13, s28
	v_perm_b32 v6, v6, v7, s29
	global_store_dword v[4:5], v6, off offset:2048 nt
	v_and_b32_e32 v6, 0xffff0000, v11
	v_lshlrev_b32_e32 v7, 16, v11
	v_fmaak_f32 v6, v6, v16, 0x4b400000
	v_fmaak_f32 v7, v7, v16, 0x4b400000
	v_perm_b32 v6, v6, v7, s28
	v_and_b32_e32 v7, 0xffff0000, v9
	v_lshlrev_b32_e32 v9, 16, v9
	v_fmaak_f32 v7, v7, v16, 0x4b400000
	v_fmaak_f32 v9, v9, v16, 0x4b400000
	v_perm_b32 v7, v7, v9, s28
	v_perm_b32 v6, v6, v7, s29
	global_store_dword v[4:5], v6, off offset:2304 nt
	v_and_b32_e32 v6, 0xffff0000, v12
	v_lshlrev_b32_e32 v7, 16, v12
	v_fmaak_f32 v6, v6, v16, 0x4b400000
	v_fmaak_f32 v7, v7, v16, 0x4b400000
	v_perm_b32 v6, v6, v7, s28
	v_and_b32_e32 v7, 0xffff0000, v10
	v_lshlrev_b32_e32 v9, 16, v10
	v_fmaak_f32 v7, v7, v16, 0x4b400000
	v_fmaak_f32 v9, v9, v16, 0x4b400000
	v_perm_b32 v7, v7, v9, s28
	v_perm_b32 v6, v6, v7, s29
	global_store_dword v[4:5], v6, off offset:2560 nt
	s_and_saveexec_b64 s[18:19], s[6:7]
	s_cbranch_execz .LBB0_908
	s_add_u32 s36, s8, s2
	s_addc_u32 s37, s9, s3
	v_mul_f32_e32 v4, 0x3c010204, v8
	global_store_dword v85, v4, s[36:37] nt
	s_branch .LBB0_908
